# X40: K-loop load segments - the wait state between each M0 write and its LDS-DMA load is filled with one of the segment's ds_read_b128 instead of s_nop
# baseline (speedup 1.0000x reference)
; #define PG8_STAGE(bufoff, gbase, voff) do { _Pragma("unroll") for (int _i = 0; _i < 2; ++_i) \
;         __builtin_amdgcn_global_load_lds((const unsigned*)((const char*)(gbase) + (voff)[_i]), (PG8_LAS unsigned*)(lds + (bufoff) + ldsw + _i * 8192), 16, 0, 0); } while (0)
; #define PG8_LDA(dst, b, h) do { _Pragma("unroll") for (int m = 0; m < 4; ++m) _Pragma("unroll") for (int k = 0; k < 2; ++k) dst[m][k] = *(const PG8_LAS bf16x8*)(lds + PG8_SA(b, h) + aoff + m * 2048 + k * 1024); } while (0)
; #define PG8_LDB(dst, b, h) do { _Pragma("unroll") for (int n = 0; n < 2; ++n) _Pragma("unroll") for (int k = 0; k < 2; ++k) dst[n][k] = *(const PG8_LAS bf16x8*)(lds + PG8_SB(b, h) + boff + n * 2048 + k * 1024); } while (0)
; #define PG8_WAIT_V(n) asm volatile("s_waitcnt vmcnt(" #n ")" ::: "memory")
; #define PG8_WAIT_L(n) asm volatile("s_waitcnt lgkmcnt(" #n ")" ::: "memory")
; #define PG8_BAR __builtin_amdgcn_s_barrier()
; #define PG8_SCHED __builtin_amdgcn_sched_barrier(0)
; template <class Epi, class Sched, bool ALIGN_EPI = false, bool SP2 = false>
; __device__ __forceinline__ void gemm_phase(PG8_LAS unsigned char* lds, const Gemm g, const Sched& S, const Epi& E) {
;     ...
;         const char* nA = has_next ? (const char*)g.A + (size_t)nxt.pm * tstep : cA; const char* nB = has_next ? (const char*)g.Bt + (size_t)nxt.pn * tstep : cB;
;         for (int t = 0; t < nt; t += 2) {
;             const bool last = (t == nt - 2);
;             const char* a1 = cA + (size_t)(t + 1) * kstep;
;             const char* a2 = last ? nA : cA + (size_t)(t + 2) * kstep; const char* b2 = last ? nB : cB + (size_t)(t + 2) * kstep;
;             const char* a3 = a2 + kstep; const char* b3 = b2 + kstep;
;             if (last && has_next) S.a_ready(nxt);
;             if constexpr (SP2) {
;             PG8_LDB(B0, 0, 0); PG8_LDB(B1, 0, 1); PG8_SCHED; PG8_LDA(At, 0, 0); PG8_STAGE(PG8_SA(1, 1), a1 + hstep, voffA);
;             PG8_WAIT_V(8); PG8_WAIT_L(0); PG8_BAR; PG8_MMA(0, 0, At, B0); PG8_MMA(0, 1, At, B1); PG8_BAR; PG8_SCHED;
;             PG8_LDA(At, 0, 1); PG8_STAGE(PG8_SB(0, 0), b2, voffB); PG8_STAGE(PG8_SB(0, 1), b2 + hstep, voffB); PG8_STAGE(PG8_SA(0, 0), a2, voffA);
;             PG8_WAIT_V(8); PG8_WAIT_L(0); PG8_BAR; PG8_MMA(1, 0, At, B0); PG8_MMA(1, 1, At, B1); PG8_BAR; PG8_SCHED;
.LBB0_216:
	ds_read_b128 v[144:147], v152
	ds_read_b128 v[148:151], v152 offset:1024
	ds_read_b128 v[168:171], v152 offset:2048
	ds_read_b128 v[172:175], v152 offset:3072
	ds_read_b128 v[176:179], v153
	ds_read_b128 v[180:183], v153 offset:1024
	ds_read_b128 v[184:187], v153 offset:2048
	ds_read_b128 v[188:191], v153 offset:3072
	ds_read_b128 v[212:215], v157
	ds_read_b128 v[216:219], v157 offset:1024
	ds_read_b128 v[220:223], v157 offset:2048
	ds_read_b128 v[224:227], v157 offset:3072
	ds_read_b128 v[228:231], v157 offset:4096
	ds_read_b128 v[232:235], v157 offset:5120
	ds_read_b128 v[236:239], v157 offset:6144
	ds_read_b128 v[240:243], v157 offset:7168
	s_add_i32 m0, s66, 0xc000
	s_add_u32 s22, s54, 0xfff80080
	s_addc_u32 s23, s55, -1
	global_load_lds_dwordx4 v140, s[54:55]
	s_add_i32 m0, s66, 0xe000
	s_add_i32 s34, 0, 0x10000
	global_load_lds_dwordx4 v142, s[54:55]
	s_cmp_eq_u32 s20, 28
	s_cselect_b32 s57, s47, s23
	s_cselect_b32 s56, vcc_lo, s22
	s_cselect_b32 s23, s49, s77
	s_cselect_b32 s22, vcc_hi, s71
	s_add_i32 s4, 0, 0x14000
	s_waitcnt vmcnt(8)
	s_waitcnt lgkmcnt(0)
	s_barrier
	v_mfma_f32_16x16x32_bf16 v[126:129], v[144:147], v[212:215], v[126:129]
	v_mfma_f32_16x16x32_bf16 v[126:129], v[148:151], v[216:219], v[126:129]
	v_mfma_f32_16x16x32_bf16 v[118:121], v[168:171], v[212:215], v[118:121]
	v_mfma_f32_16x16x32_bf16 v[118:121], v[172:175], v[216:219], v[118:121]
	v_mfma_f32_16x16x32_bf16 v[130:133], v[176:179], v[212:215], v[130:133]
	v_mfma_f32_16x16x32_bf16 v[130:133], v[180:183], v[216:219], v[130:133]
	v_mfma_f32_16x16x32_bf16 v[122:125], v[184:187], v[212:215], v[122:125]
	v_mfma_f32_16x16x32_bf16 v[122:125], v[188:191], v[216:219], v[122:125]
	v_mfma_f32_16x16x32_bf16 v[106:109], v[184:187], v[220:223], v[106:109]
	v_mfma_f32_16x16x32_bf16 v[106:109], v[188:191], v[224:227], v[106:109]
	v_mfma_f32_16x16x32_bf16 v[114:117], v[176:179], v[220:223], v[114:117]
	v_mfma_f32_16x16x32_bf16 v[114:117], v[180:183], v[224:227], v[114:117]
	v_mfma_f32_16x16x32_bf16 v[102:105], v[168:171], v[220:223], v[102:105]
	v_mfma_f32_16x16x32_bf16 v[102:105], v[172:175], v[224:227], v[102:105]
	v_mfma_f32_16x16x32_bf16 v[110:113], v[144:147], v[220:223], v[110:113]
	v_mfma_f32_16x16x32_bf16 v[110:113], v[148:151], v[224:227], v[110:113]
	v_mfma_f32_16x16x32_bf16 v[94:97], v[144:147], v[228:231], v[94:97]
	v_mfma_f32_16x16x32_bf16 v[94:97], v[148:151], v[232:235], v[94:97]
	v_mfma_f32_16x16x32_bf16 v[86:89], v[168:171], v[228:231], v[86:89]
	v_mfma_f32_16x16x32_bf16 v[86:89], v[172:175], v[232:235], v[86:89]
	v_mfma_f32_16x16x32_bf16 v[98:101], v[176:179], v[228:231], v[98:101]
	v_mfma_f32_16x16x32_bf16 v[98:101], v[180:183], v[232:235], v[98:101]
	v_mfma_f32_16x16x32_bf16 v[90:93], v[184:187], v[228:231], v[90:93]
	v_mfma_f32_16x16x32_bf16 v[90:93], v[188:191], v[232:235], v[90:93]
	v_mfma_f32_16x16x32_bf16 v[74:77], v[184:187], v[236:239], v[74:77]
	v_mfma_f32_16x16x32_bf16 v[74:77], v[188:191], v[240:243], v[74:77]
	v_mfma_f32_16x16x32_bf16 v[82:85], v[176:179], v[236:239], v[82:85]
	v_mfma_f32_16x16x32_bf16 v[82:85], v[180:183], v[240:243], v[82:85]
	v_mfma_f32_16x16x32_bf16 v[70:73], v[168:171], v[236:239], v[70:73]
	v_mfma_f32_16x16x32_bf16 v[70:73], v[172:175], v[240:243], v[70:73]
	v_mfma_f32_16x16x32_bf16 v[78:81], v[144:147], v[236:239], v[78:81]
	v_mfma_f32_16x16x32_bf16 v[78:81], v[148:151], v[240:243], v[78:81]
	s_barrier
	ds_read_b128 v[212:215], v157 offset:16384
	ds_read_b128 v[216:219], v157 offset:17408
	ds_read_b128 v[220:223], v157 offset:18432
	ds_read_b128 v[224:227], v157 offset:19456
	s_add_i32 s5, s34, s65
	s_mov_b32 m0, s5
	s_add_u32 s34, s22, 0x80000
	s_addc_u32 s35, s23, 0
	global_load_lds_dwordx4 v4, s[22:23]
	s_add_i32 m0, s5, 0x2000
	s_add_i32 s4, s4, s65
	global_load_lds_dwordx4 v2, s[22:23]
	s_mov_b32 m0, s4
	ds_read_b128 v[228:231], v157 offset:20480
	global_load_lds_dwordx4 v4, s[34:35]
	s_add_i32 m0, s4, 0x2000
	ds_read_b128 v[232:235], v157 offset:21504
	global_load_lds_dwordx4 v2, s[34:35]
	s_mov_b32 m0, s66
	ds_read_b128 v[236:239], v157 offset:22528
	global_load_lds_dwordx4 v136, s[56:57]
	s_mov_b32 m0, s67
	ds_read_b128 v[240:243], v157 offset:23552
	global_load_lds_dwordx4 v134, s[56:57]
	s_waitcnt vmcnt(8)
	s_waitcnt lgkmcnt(0)
	s_barrier
	v_mfma_f32_16x16x32_bf16 v[62:65], v[144:147], v[212:215], v[62:65]
	v_mfma_f32_16x16x32_bf16 v[62:65], v[148:151], v[216:219], v[62:65]
	v_mfma_f32_16x16x32_bf16 v[54:57], v[168:171], v[212:215], v[54:57]
	v_mfma_f32_16x16x32_bf16 v[54:57], v[172:175], v[216:219], v[54:57]
	v_mfma_f32_16x16x32_bf16 v[66:69], v[176:179], v[212:215], v[66:69]
	v_mfma_f32_16x16x32_bf16 v[66:69], v[180:183], v[216:219], v[66:69]
	v_mfma_f32_16x16x32_bf16 v[58:61], v[184:187], v[212:215], v[58:61]
	v_mfma_f32_16x16x32_bf16 v[58:61], v[188:191], v[216:219], v[58:61]
	v_mfma_f32_16x16x32_bf16 v[42:45], v[184:187], v[220:223], v[42:45]
	v_mfma_f32_16x16x32_bf16 v[42:45], v[188:191], v[224:227], v[42:45]
	v_mfma_f32_16x16x32_bf16 v[50:53], v[176:179], v[220:223], v[50:53]
	v_mfma_f32_16x16x32_bf16 v[50:53], v[180:183], v[224:227], v[50:53]
	v_mfma_f32_16x16x32_bf16 v[38:41], v[168:171], v[220:223], v[38:41]
	v_mfma_f32_16x16x32_bf16 v[38:41], v[172:175], v[224:227], v[38:41]
	v_mfma_f32_16x16x32_bf16 v[46:49], v[144:147], v[220:223], v[46:49]
	v_mfma_f32_16x16x32_bf16 v[46:49], v[148:151], v[224:227], v[46:49]
	v_mfma_f32_16x16x32_bf16 v[30:33], v[144:147], v[228:231], v[30:33]
	v_mfma_f32_16x16x32_bf16 v[30:33], v[148:151], v[232:235], v[30:33]
	v_mfma_f32_16x16x32_bf16 v[22:25], v[168:171], v[228:231], v[22:25]
	v_mfma_f32_16x16x32_bf16 v[22:25], v[172:175], v[232:235], v[22:25]
	v_mfma_f32_16x16x32_bf16 v[34:37], v[176:179], v[228:231], v[34:37]
	v_mfma_f32_16x16x32_bf16 v[34:37], v[180:183], v[232:235], v[34:37]
	v_mfma_f32_16x16x32_bf16 v[26:29], v[184:187], v[228:231], v[26:29]
	v_mfma_f32_16x16x32_bf16 v[26:29], v[188:191], v[232:235], v[26:29]
	v_mfma_f32_16x16x32_bf16 v[10:13], v[184:187], v[236:239], v[10:13]
	v_mfma_f32_16x16x32_bf16 v[10:13], v[188:191], v[240:243], v[10:13]
	v_mfma_f32_16x16x32_bf16 v[18:21], v[176:179], v[236:239], v[18:21]
	v_mfma_f32_16x16x32_bf16 v[18:21], v[180:183], v[240:243], v[18:21]
	v_mfma_f32_16x16x32_bf16 v[6:9], v[168:171], v[236:239], v[6:9]
	v_mfma_f32_16x16x32_bf16 v[6:9], v[172:175], v[240:243], v[6:9]
	v_mfma_f32_16x16x32_bf16 v[14:17], v[144:147], v[236:239], v[14:17]
	v_mfma_f32_16x16x32_bf16 v[14:17], v[148:151], v[240:243], v[14:17]
	s_barrier
; #define PG8_STAGE(bufoff, gbase, voff) do { _Pragma("unroll") for (int _i = 0; _i < 2; ++_i) \
;         __builtin_amdgcn_global_load_lds((const unsigned*)((const char*)(gbase) + (voff)[_i]), (PG8_LAS unsigned*)(lds + (bufoff) + ldsw + _i * 8192), 16, 0, 0); } while (0)
; #define PG8_LDA(dst, b, h) do { _Pragma("unroll") for (int m = 0; m < 4; ++m) _Pragma("unroll") for (int k = 0; k < 2; ++k) dst[m][k] = *(const PG8_LAS bf16x8*)(lds + PG8_SA(b, h) + aoff + m * 2048 + k * 1024); } while (0)
; #define PG8_LDB(dst, b, h) do { _Pragma("unroll") for (int n = 0; n < 2; ++n) _Pragma("unroll") for (int k = 0; k < 2; ++k) dst[n][k] = *(const PG8_LAS bf16x8*)(lds + PG8_SB(b, h) + boff + n * 2048 + k * 1024); } while (0)
; #define PG8_MMA(ai, bj, At, Bt) do { __builtin_amdgcn_s_setprio(1); _Pragma("unroll") for (int m = 0; m < 4; ++m) _Pragma("unroll") for (int n = 0; n < 2; ++n) _Pragma("unroll") for (int k = 0; k < 2; ++k) \
;         acc[ai][bj][m][n] = __builtin_amdgcn_mfma_f32_16x16x32_bf16(Bt[n][k], At[m][k], acc[ai][bj][m][n], 0, 0, 0); __builtin_amdgcn_s_setprio(0); } while (0)
; #define PG8_WAIT_V(n) asm volatile("s_waitcnt vmcnt(" #n ")" ::: "memory")
; #define PG8_WAIT_L(n) asm volatile("s_waitcnt lgkmcnt(" #n ")" ::: "memory")
; #define PG8_BAR __builtin_amdgcn_s_barrier()
; #define PG8_SCHED __builtin_amdgcn_sched_barrier(0)
; template <class Epi, class Sched, bool ALIGN_EPI = false, bool SP2 = false>
; __device__ __forceinline__ void gemm_phase(PG8_LAS unsigned char* lds, const Gemm g, const Sched& S, const Epi& E) {
;     ...
;         for (int t = 0; t < nt; t += 2) {
;             const bool last = (t == nt - 2);
;             const char* a1 = cA + (size_t)(t + 1) * kstep;
;             const char* a2 = last ? nA : cA + (size_t)(t + 2) * kstep; const char* b2 = last ? nB : cB + (size_t)(t + 2) * kstep;
;     ...
;             PG8_LDB(B0, 1, 0); PG8_LDB(B1, 1, 1); PG8_SCHED; PG8_LDA(At, 1, 0); PG8_STAGE(PG8_SA(0, 1), a2 + hstep, voffA);
;             PG8_WAIT_V(8); PG8_WAIT_L(0); PG8_BAR; PG8_MMA(0, 0, At, B0); PG8_MMA(0, 1, At, B1); PG8_BAR; PG8_SCHED;
;             PG8_LDA(At, 1, 1); PG8_STAGE(PG8_SB(1, 0), b3, voffB); PG8_STAGE(PG8_SB(1, 1), b3 + hstep, voffB); PG8_STAGE(PG8_SA(1, 0), a3, voffA);
;             PG8_WAIT_V(8); PG8_WAIT_L(0); PG8_BAR; PG8_MMA(1, 0, At, B0); PG8_MMA(1, 1, At, B1); PG8_BAR; PG8_SCHED;
	ds_read_b128 v[144:147], v192
	ds_read_b128 v[148:151], v192 offset:1024
	ds_read_b128 v[168:171], v192 offset:2048
	ds_read_b128 v[172:175], v192 offset:3072
	ds_read_b128 v[176:179], v193
	ds_read_b128 v[180:183], v193 offset:1024
	ds_read_b128 v[184:187], v193 offset:2048
	ds_read_b128 v[188:191], v193 offset:3072
	ds_read_b128 v[212:215], v157 offset:32768
	ds_read_b128 v[216:219], v157 offset:33792
	ds_read_b128 v[220:223], v157 offset:34816
	ds_read_b128 v[224:227], v157 offset:35840
	ds_read_b128 v[228:231], v157 offset:36864
	ds_read_b128 v[232:235], v157 offset:37888
	ds_read_b128 v[236:239], v157 offset:38912
	ds_read_b128 v[240:243], v157 offset:39936
	s_add_u32 s34, s56, 0x80000
	s_addc_u32 s35, s57, 0
	s_mov_b32 m0, s60
	s_add_i32 s4, 0, 0x18000
	global_load_lds_dwordx4 v136, s[34:35]
	s_mov_b32 m0, s2
	s_add_i32 s5, 0, 0x1c000
	global_load_lds_dwordx4 v134, s[34:35]
	s_waitcnt vmcnt(8)
	s_waitcnt lgkmcnt(0)
	s_barrier
	v_mfma_f32_16x16x32_bf16 v[126:129], v[144:147], v[212:215], v[126:129]
	v_mfma_f32_16x16x32_bf16 v[126:129], v[148:151], v[216:219], v[126:129]
	v_mfma_f32_16x16x32_bf16 v[118:121], v[168:171], v[212:215], v[118:121]
	v_mfma_f32_16x16x32_bf16 v[118:121], v[172:175], v[216:219], v[118:121]
	v_mfma_f32_16x16x32_bf16 v[130:133], v[176:179], v[212:215], v[130:133]
	v_mfma_f32_16x16x32_bf16 v[130:133], v[180:183], v[216:219], v[130:133]
	v_mfma_f32_16x16x32_bf16 v[122:125], v[184:187], v[212:215], v[122:125]
	v_mfma_f32_16x16x32_bf16 v[122:125], v[188:191], v[216:219], v[122:125]
	v_mfma_f32_16x16x32_bf16 v[106:109], v[184:187], v[220:223], v[106:109]
	v_mfma_f32_16x16x32_bf16 v[106:109], v[188:191], v[224:227], v[106:109]
	v_mfma_f32_16x16x32_bf16 v[114:117], v[176:179], v[220:223], v[114:117]
	v_mfma_f32_16x16x32_bf16 v[114:117], v[180:183], v[224:227], v[114:117]
	v_mfma_f32_16x16x32_bf16 v[102:105], v[168:171], v[220:223], v[102:105]
	v_mfma_f32_16x16x32_bf16 v[102:105], v[172:175], v[224:227], v[102:105]
	v_mfma_f32_16x16x32_bf16 v[110:113], v[144:147], v[220:223], v[110:113]
	v_mfma_f32_16x16x32_bf16 v[110:113], v[148:151], v[224:227], v[110:113]
	v_mfma_f32_16x16x32_bf16 v[94:97], v[144:147], v[228:231], v[94:97]
	v_mfma_f32_16x16x32_bf16 v[94:97], v[148:151], v[232:235], v[94:97]
	v_mfma_f32_16x16x32_bf16 v[86:89], v[168:171], v[228:231], v[86:89]
	v_mfma_f32_16x16x32_bf16 v[86:89], v[172:175], v[232:235], v[86:89]
	v_mfma_f32_16x16x32_bf16 v[98:101], v[176:179], v[228:231], v[98:101]
	v_mfma_f32_16x16x32_bf16 v[98:101], v[180:183], v[232:235], v[98:101]
	v_mfma_f32_16x16x32_bf16 v[90:93], v[184:187], v[228:231], v[90:93]
	v_mfma_f32_16x16x32_bf16 v[90:93], v[188:191], v[232:235], v[90:93]
	v_mfma_f32_16x16x32_bf16 v[74:77], v[184:187], v[236:239], v[74:77]
	v_mfma_f32_16x16x32_bf16 v[74:77], v[188:191], v[240:243], v[74:77]
	v_mfma_f32_16x16x32_bf16 v[82:85], v[176:179], v[236:239], v[82:85]
	v_mfma_f32_16x16x32_bf16 v[82:85], v[180:183], v[240:243], v[82:85]
	v_mfma_f32_16x16x32_bf16 v[70:73], v[168:171], v[236:239], v[70:73]
	v_mfma_f32_16x16x32_bf16 v[70:73], v[172:175], v[240:243], v[70:73]
	v_mfma_f32_16x16x32_bf16 v[78:81], v[144:147], v[236:239], v[78:81]
	v_mfma_f32_16x16x32_bf16 v[78:81], v[148:151], v[240:243], v[78:81]
	s_barrier
	ds_read_b128 v[212:215], v157 offset:49152
	ds_read_b128 v[216:219], v157 offset:50176
	ds_read_b128 v[220:223], v157 offset:51200
	s_add_i32 s4, s4, s65
	s_add_i32 m0, s4, 0xffffff80
	ds_read_b128 v[224:227], v157 offset:52224
	global_load_lds_dwordx4 v4, s[22:23] offset:128
	s_add_i32 m0, s4, 0x1f80
	s_add_i32 s4, s5, s65
	global_load_lds_dwordx4 v2, s[22:23] offset:128
	s_add_u32 s22, s22, 0x80080
	s_addc_u32 s23, s23, 0
	s_mov_b32 m0, s4
	ds_read_b128 v[228:231], v157 offset:53248
	global_load_lds_dwordx4 v4, s[22:23]
	s_add_i32 m0, s4, 0x2000
	ds_read_b128 v[232:235], v157 offset:54272
	global_load_lds_dwordx4 v2, s[22:23]
	s_add_i32 m0, s3, 0xffffff80
	ds_read_b128 v[236:239], v157 offset:55296
	global_load_lds_dwordx4 v136, s[56:57] offset:128
	s_add_i32 m0, s75, 0xffffff80
	ds_read_b128 v[240:243], v157 offset:56320
	global_load_lds_dwordx4 v134, s[56:57] offset:128
	s_waitcnt vmcnt(8)
	s_waitcnt lgkmcnt(0)
	s_barrier
	v_mfma_f32_16x16x32_bf16 v[62:65], v[144:147], v[212:215], v[62:65]
	v_mfma_f32_16x16x32_bf16 v[62:65], v[148:151], v[216:219], v[62:65]
	v_mfma_f32_16x16x32_bf16 v[54:57], v[168:171], v[212:215], v[54:57]
	v_mfma_f32_16x16x32_bf16 v[54:57], v[172:175], v[216:219], v[54:57]
	v_mfma_f32_16x16x32_bf16 v[66:69], v[176:179], v[212:215], v[66:69]
	v_mfma_f32_16x16x32_bf16 v[66:69], v[180:183], v[216:219], v[66:69]
	v_mfma_f32_16x16x32_bf16 v[58:61], v[184:187], v[212:215], v[58:61]
	v_mfma_f32_16x16x32_bf16 v[58:61], v[188:191], v[216:219], v[58:61]
	v_mfma_f32_16x16x32_bf16 v[42:45], v[184:187], v[220:223], v[42:45]
	v_mfma_f32_16x16x32_bf16 v[42:45], v[188:191], v[224:227], v[42:45]
	v_mfma_f32_16x16x32_bf16 v[50:53], v[176:179], v[220:223], v[50:53]
	v_mfma_f32_16x16x32_bf16 v[50:53], v[180:183], v[224:227], v[50:53]
	v_mfma_f32_16x16x32_bf16 v[38:41], v[168:171], v[220:223], v[38:41]
	v_mfma_f32_16x16x32_bf16 v[38:41], v[172:175], v[224:227], v[38:41]
	v_mfma_f32_16x16x32_bf16 v[46:49], v[144:147], v[220:223], v[46:49]
	v_mfma_f32_16x16x32_bf16 v[46:49], v[148:151], v[224:227], v[46:49]
	v_mfma_f32_16x16x32_bf16 v[30:33], v[144:147], v[228:231], v[30:33]
	v_mfma_f32_16x16x32_bf16 v[30:33], v[148:151], v[232:235], v[30:33]
	v_mfma_f32_16x16x32_bf16 v[22:25], v[168:171], v[228:231], v[22:25]
	v_mfma_f32_16x16x32_bf16 v[22:25], v[172:175], v[232:235], v[22:25]
	v_mfma_f32_16x16x32_bf16 v[34:37], v[176:179], v[228:231], v[34:37]
	v_mfma_f32_16x16x32_bf16 v[34:37], v[180:183], v[232:235], v[34:37]
	v_mfma_f32_16x16x32_bf16 v[26:29], v[184:187], v[228:231], v[26:29]
	v_mfma_f32_16x16x32_bf16 v[26:29], v[188:191], v[232:235], v[26:29]
	v_mfma_f32_16x16x32_bf16 v[10:13], v[184:187], v[236:239], v[10:13]
	v_mfma_f32_16x16x32_bf16 v[10:13], v[188:191], v[240:243], v[10:13]
	v_mfma_f32_16x16x32_bf16 v[18:21], v[176:179], v[236:239], v[18:21]
	v_mfma_f32_16x16x32_bf16 v[18:21], v[180:183], v[240:243], v[18:21]
	v_mfma_f32_16x16x32_bf16 v[6:9], v[168:171], v[236:239], v[6:9]
	v_mfma_f32_16x16x32_bf16 v[6:9], v[172:175], v[240:243], v[6:9]
	v_mfma_f32_16x16x32_bf16 v[14:17], v[144:147], v[236:239], v[14:17]
	v_mfma_f32_16x16x32_bf16 v[14:17], v[148:151], v[240:243], v[14:17]
	s_barrier
	s_add_i32 s20, s20, 2
	s_add_u32 s54, s54, 0x100
	s_addc_u32 s55, s55, 0
	s_add_u32 s71, s71, 0x100
	s_addc_u32 s77, s77, 0
	s_cmp_gt_u32 s20, 29
	s_cbranch_scc0 .LBB0_216
	s_and_b64 vcc, exec, s[44:45]
	s_movk_i32 s77, 0x6000
	s_mov_b32 s71, 0x44800000
	s_cbranch_vccz .LBB0_219
	s_barrier

; #define PG8_STAGE(bufoff, gbase, voff) do { _Pragma("unroll") for (int _i = 0; _i < 2; ++_i) \
;         __builtin_amdgcn_global_load_lds((const unsigned*)((const char*)(gbase) + (voff)[_i]), (PG8_LAS unsigned*)(lds + (bufoff) + ldsw + _i * 8192), 16, 0, 0); } while (0)
; #define PG8_LDA(dst, b, h) do { _Pragma("unroll") for (int m = 0; m < 4; ++m) _Pragma("unroll") for (int k = 0; k < 2; ++k) dst[m][k] = *(const PG8_LAS bf16x8*)(lds + PG8_SA(b, h) + aoff + m * 2048 + k * 1024); } while (0)
; #define PG8_LDB(dst, b, h) do { _Pragma("unroll") for (int n = 0; n < 2; ++n) _Pragma("unroll") for (int k = 0; k < 2; ++k) dst[n][k] = *(const PG8_LAS bf16x8*)(lds + PG8_SB(b, h) + boff + n * 2048 + k * 1024); } while (0)
; #define PG8_MMA(ai, bj, At, Bt) do { __builtin_amdgcn_s_setprio(1); _Pragma("unroll") for (int m = 0; m < 4; ++m) _Pragma("unroll") for (int n = 0; n < 2; ++n) _Pragma("unroll") for (int k = 0; k < 2; ++k) \
;         acc[ai][bj][m][n] = __builtin_amdgcn_mfma_f32_16x16x32_bf16(Bt[n][k], At[m][k], acc[ai][bj][m][n], 0, 0, 0); __builtin_amdgcn_s_setprio(0); } while (0)
; #define PG8_WAIT_V(n) asm volatile("s_waitcnt vmcnt(" #n ")" ::: "memory")
; #define PG8_WAIT_L(n) asm volatile("s_waitcnt lgkmcnt(" #n ")" ::: "memory")
; template <class Epi, class Sched, bool ALIGN_EPI = false, bool SP2 = false>
; __device__ __forceinline__ void gemm_phase(PG8_LAS unsigned char* lds, const Gemm g, const Sched& S, const Epi& E) {
;     ...
;             const bool last = (t == nt - 2);
;             const char* a1 = cA + (size_t)(t + 1) * kstep;
;             const char* a2 = last ? nA : cA + (size_t)(t + 2) * kstep; const char* b2 = last ? nB : cB + (size_t)(t + 2) * kstep;
;             const char* a3 = a2 + kstep; const char* b3 = b2 + kstep;
;             if (last && has_next) S.a_ready(nxt);
;             if constexpr (SP2) {
;             PG8_LDB(B0, 0, 0); PG8_LDB(B1, 0, 1); PG8_SCHED; PG8_LDA(At, 0, 0); PG8_STAGE(PG8_SA(1, 1), a1 + hstep, voffA);
;             PG8_WAIT_V(8); PG8_WAIT_L(0); PG8_BAR; PG8_MMA(0, 0, At, B0); PG8_MMA(0, 1, At, B1); PG8_BAR; PG8_SCHED;
;             PG8_LDA(At, 0, 1); PG8_STAGE(PG8_SB(0, 0), b2, voffB); PG8_STAGE(PG8_SB(0, 1), b2 + hstep, voffB); PG8_STAGE(PG8_SA(0, 0), a2, voffA);
;             PG8_WAIT_V(8); PG8_WAIT_L(0); PG8_BAR; PG8_MMA(1, 0, At, B0); PG8_MMA(1, 1, At, B1); PG8_BAR; PG8_SCHED;
.LBB0_299:
	s_add_u32 s50, s22, 0x100
	s_addc_u32 s51, s23, 0
	s_add_i32 s4, 0, 0x10000
	s_cmpk_eq_i32 s20, 0x54
	s_cselect_b32 s55, s41, s51
	s_cselect_b32 s54, s40, s50
	s_cselect_b32 s53, s49, s69
	s_cselect_b32 s52, s48, s33
	s_add_i32 s5, 0, 0x14000
	ds_read_b128 v[134:137], v236
	ds_read_b128 v[138:141], v236 offset:1024
	ds_read_b128 v[142:145], v236 offset:2048
	ds_read_b128 v[146:149], v236 offset:3072
	ds_read_b128 v[150:153], v237
	ds_read_b128 v[154:157], v237 offset:1024
	ds_read_b128 v[176:179], v237 offset:2048
	ds_read_b128 v[180:183], v237 offset:3072
	s_add_i32 m0, s56, 0xc000
	ds_read_b128 v[184:187], v188
	ds_read_b128 v[190:193], v188 offset:1024
	ds_read_b128 v[212:215], v188 offset:2048
	ds_read_b128 v[216:219], v188 offset:3072
	ds_read_b128 v[220:223], v188 offset:4096
	ds_read_b128 v[224:227], v188 offset:5120
	ds_read_b128 v[228:231], v188 offset:6144
	global_load_lds_dwordx4 v172, s[22:23]
	s_add_i32 m0, s56, 0xe000
	ds_read_b128 v[232:235], v188 offset:7168
	global_load_lds_dwordx4 v174, s[22:23]
	s_waitcnt vmcnt(8)
	s_waitcnt lgkmcnt(0)
	s_barrier
	v_mfma_f32_16x16x32_bf16 v[122:125], v[134:137], v[184:187], v[122:125]
	v_mfma_f32_16x16x32_bf16 v[122:125], v[138:141], v[190:193], v[122:125]
	v_mfma_f32_16x16x32_bf16 v[118:121], v[142:145], v[184:187], v[118:121]
	v_mfma_f32_16x16x32_bf16 v[118:121], v[146:149], v[190:193], v[118:121]
	v_mfma_f32_16x16x32_bf16 v[130:133], v[150:153], v[184:187], v[130:133]
	v_mfma_f32_16x16x32_bf16 v[130:133], v[154:157], v[190:193], v[130:133]
	v_mfma_f32_16x16x32_bf16 v[126:129], v[176:179], v[184:187], v[126:129]
	v_mfma_f32_16x16x32_bf16 v[126:129], v[180:183], v[190:193], v[126:129]
	v_mfma_f32_16x16x32_bf16 v[102:105], v[176:179], v[212:215], v[102:105]
	v_mfma_f32_16x16x32_bf16 v[102:105], v[180:183], v[216:219], v[102:105]
	v_mfma_f32_16x16x32_bf16 v[106:109], v[150:153], v[212:215], v[106:109]
	v_mfma_f32_16x16x32_bf16 v[106:109], v[154:157], v[216:219], v[106:109]
	v_mfma_f32_16x16x32_bf16 v[110:113], v[142:145], v[212:215], v[110:113]
	v_mfma_f32_16x16x32_bf16 v[110:113], v[146:149], v[216:219], v[110:113]
	v_mfma_f32_16x16x32_bf16 v[114:117], v[134:137], v[212:215], v[114:117]
	v_mfma_f32_16x16x32_bf16 v[114:117], v[138:141], v[216:219], v[114:117]
	v_mfma_f32_16x16x32_bf16 v[98:101], v[134:137], v[220:223], v[98:101]
	v_mfma_f32_16x16x32_bf16 v[98:101], v[138:141], v[224:227], v[98:101]
	v_mfma_f32_16x16x32_bf16 v[94:97], v[142:145], v[220:223], v[94:97]
	v_mfma_f32_16x16x32_bf16 v[94:97], v[146:149], v[224:227], v[94:97]
	v_mfma_f32_16x16x32_bf16 v[90:93], v[150:153], v[220:223], v[90:93]
	v_mfma_f32_16x16x32_bf16 v[90:93], v[154:157], v[224:227], v[90:93]
	v_mfma_f32_16x16x32_bf16 v[86:89], v[176:179], v[220:223], v[86:89]
	v_mfma_f32_16x16x32_bf16 v[86:89], v[180:183], v[224:227], v[86:89]
	v_mfma_f32_16x16x32_bf16 v[70:73], v[176:179], v[228:231], v[70:73]
	v_mfma_f32_16x16x32_bf16 v[70:73], v[180:183], v[232:235], v[70:73]
	v_mfma_f32_16x16x32_bf16 v[74:77], v[150:153], v[228:231], v[74:77]
	v_mfma_f32_16x16x32_bf16 v[74:77], v[154:157], v[232:235], v[74:77]
	v_mfma_f32_16x16x32_bf16 v[78:81], v[142:145], v[228:231], v[78:81]
	v_mfma_f32_16x16x32_bf16 v[78:81], v[146:149], v[232:235], v[78:81]
	v_mfma_f32_16x16x32_bf16 v[82:85], v[134:137], v[228:231], v[82:85]
	v_mfma_f32_16x16x32_bf16 v[82:85], v[138:141], v[232:235], v[82:85]
	s_barrier
	s_add_i32 s4, s4, s24
	s_mov_b32 m0, s4
	ds_read_b128 v[184:187], v188 offset:16384
	ds_read_b128 v[190:193], v188 offset:17408
	ds_read_b128 v[212:215], v188 offset:18432
	ds_read_b128 v[216:219], v188 offset:19456
	global_load_lds_dwordx4 v4, s[52:53]
	s_add_i32 m0, s4, 0x2000
	s_add_u32 s22, s52, 0x160000
	s_addc_u32 s23, s53, 0
	s_add_i32 s4, s5, s24
	global_load_lds_dwordx4 v170, s[52:53]
	s_mov_b32 m0, s4
	ds_read_b128 v[220:223], v188 offset:20480
	global_load_lds_dwordx4 v4, s[22:23]
	s_add_i32 m0, s4, 0x2000
	ds_read_b128 v[224:227], v188 offset:21504
	global_load_lds_dwordx4 v170, s[22:23]
	s_mov_b32 m0, s56
	ds_read_b128 v[228:231], v188 offset:22528
	global_load_lds_dwordx4 v2, s[54:55]
	s_mov_b32 m0, s57
	ds_read_b128 v[232:235], v188 offset:23552
	global_load_lds_dwordx4 v168, s[54:55]
	s_waitcnt vmcnt(8)
	s_waitcnt lgkmcnt(0)
	s_barrier
	v_mfma_f32_16x16x32_bf16 v[58:61], v[134:137], v[184:187], v[58:61]
	v_mfma_f32_16x16x32_bf16 v[58:61], v[138:141], v[190:193], v[58:61]
	v_mfma_f32_16x16x32_bf16 v[54:57], v[142:145], v[184:187], v[54:57]
	v_mfma_f32_16x16x32_bf16 v[54:57], v[146:149], v[190:193], v[54:57]
	v_mfma_f32_16x16x32_bf16 v[66:69], v[150:153], v[184:187], v[66:69]
	v_mfma_f32_16x16x32_bf16 v[66:69], v[154:157], v[190:193], v[66:69]
	v_mfma_f32_16x16x32_bf16 v[62:65], v[176:179], v[184:187], v[62:65]
	v_mfma_f32_16x16x32_bf16 v[62:65], v[180:183], v[190:193], v[62:65]
	v_mfma_f32_16x16x32_bf16 v[38:41], v[176:179], v[212:215], v[38:41]
	v_mfma_f32_16x16x32_bf16 v[38:41], v[180:183], v[216:219], v[38:41]
	v_mfma_f32_16x16x32_bf16 v[42:45], v[150:153], v[212:215], v[42:45]
	v_mfma_f32_16x16x32_bf16 v[42:45], v[154:157], v[216:219], v[42:45]
	v_mfma_f32_16x16x32_bf16 v[46:49], v[142:145], v[212:215], v[46:49]
	v_mfma_f32_16x16x32_bf16 v[46:49], v[146:149], v[216:219], v[46:49]
	v_mfma_f32_16x16x32_bf16 v[50:53], v[134:137], v[212:215], v[50:53]
	v_mfma_f32_16x16x32_bf16 v[50:53], v[138:141], v[216:219], v[50:53]
	v_mfma_f32_16x16x32_bf16 v[34:37], v[134:137], v[220:223], v[34:37]
	v_mfma_f32_16x16x32_bf16 v[34:37], v[138:141], v[224:227], v[34:37]
	v_mfma_f32_16x16x32_bf16 v[30:33], v[142:145], v[220:223], v[30:33]
	v_mfma_f32_16x16x32_bf16 v[30:33], v[146:149], v[224:227], v[30:33]
	v_mfma_f32_16x16x32_bf16 v[26:29], v[150:153], v[220:223], v[26:29]
	v_mfma_f32_16x16x32_bf16 v[26:29], v[154:157], v[224:227], v[26:29]
	v_mfma_f32_16x16x32_bf16 v[22:25], v[176:179], v[220:223], v[22:25]
	v_mfma_f32_16x16x32_bf16 v[22:25], v[180:183], v[224:227], v[22:25]
	v_mfma_f32_16x16x32_bf16 v[6:9], v[176:179], v[228:231], v[6:9]
	v_mfma_f32_16x16x32_bf16 v[6:9], v[180:183], v[232:235], v[6:9]
	v_mfma_f32_16x16x32_bf16 v[10:13], v[150:153], v[228:231], v[10:13]
	v_mfma_f32_16x16x32_bf16 v[10:13], v[154:157], v[232:235], v[10:13]
	v_mfma_f32_16x16x32_bf16 v[14:17], v[142:145], v[228:231], v[14:17]
	v_mfma_f32_16x16x32_bf16 v[14:17], v[146:149], v[232:235], v[14:17]
	v_mfma_f32_16x16x32_bf16 v[18:21], v[134:137], v[228:231], v[18:21]
	v_mfma_f32_16x16x32_bf16 v[18:21], v[138:141], v[232:235], v[18:21]
	s_barrier
; #define PG8_STAGE(bufoff, gbase, voff) do { _Pragma("unroll") for (int _i = 0; _i < 2; ++_i) \
;         __builtin_amdgcn_global_load_lds((const unsigned*)((const char*)(gbase) + (voff)[_i]), (PG8_LAS unsigned*)(lds + (bufoff) + ldsw + _i * 8192), 16, 0, 0); } while (0)
; #define PG8_LDA(dst, b, h) do { _Pragma("unroll") for (int m = 0; m < 4; ++m) _Pragma("unroll") for (int k = 0; k < 2; ++k) dst[m][k] = *(const PG8_LAS bf16x8*)(lds + PG8_SA(b, h) + aoff + m * 2048 + k * 1024); } while (0)
; #define PG8_LDB(dst, b, h) do { _Pragma("unroll") for (int n = 0; n < 2; ++n) _Pragma("unroll") for (int k = 0; k < 2; ++k) dst[n][k] = *(const PG8_LAS bf16x8*)(lds + PG8_SB(b, h) + boff + n * 2048 + k * 1024); } while (0)
; #define PG8_MMA(ai, bj, At, Bt) do { __builtin_amdgcn_s_setprio(1); _Pragma("unroll") for (int m = 0; m < 4; ++m) _Pragma("unroll") for (int n = 0; n < 2; ++n) _Pragma("unroll") for (int k = 0; k < 2; ++k) \
;         acc[ai][bj][m][n] = __builtin_amdgcn_mfma_f32_16x16x32_bf16(Bt[n][k], At[m][k], acc[ai][bj][m][n], 0, 0, 0); __builtin_amdgcn_s_setprio(0); } while (0)
; #define PG8_WAIT_V(n) asm volatile("s_waitcnt vmcnt(" #n ")" ::: "memory")
; #define PG8_WAIT_L(n) asm volatile("s_waitcnt lgkmcnt(" #n ")" ::: "memory")
; #define PG8_BAR __builtin_amdgcn_s_barrier()
; #define PG8_SCHED __builtin_amdgcn_sched_barrier(0)
; template <class Epi, class Sched, bool ALIGN_EPI = false, bool SP2 = false>
; __device__ __forceinline__ void gemm_phase(PG8_LAS unsigned char* lds, const Gemm g, const Sched& S, const Epi& E) {
;     ...
;         for (int t = 0; t < nt; t += 2) {
;             const bool last = (t == nt - 2);
;             const char* a1 = cA + (size_t)(t + 1) * kstep;
;             const char* a2 = last ? nA : cA + (size_t)(t + 2) * kstep; const char* b2 = last ? nB : cB + (size_t)(t + 2) * kstep;
;     ...
;             PG8_LDB(B0, 1, 0); PG8_LDB(B1, 1, 1); PG8_SCHED; PG8_LDA(At, 1, 0); PG8_STAGE(PG8_SA(0, 1), a2 + hstep, voffA);
;             PG8_WAIT_V(8); PG8_WAIT_L(0); PG8_BAR; PG8_MMA(0, 0, At, B0); PG8_MMA(0, 1, At, B1); PG8_BAR; PG8_SCHED;
;             PG8_LDA(At, 1, 1); PG8_STAGE(PG8_SB(1, 0), b3, voffB); PG8_STAGE(PG8_SB(1, 1), b3 + hstep, voffB); PG8_STAGE(PG8_SA(1, 0), a3, voffA);
;             PG8_WAIT_V(8); PG8_WAIT_L(0); PG8_BAR; PG8_MMA(1, 0, At, B0); PG8_MMA(1, 1, At, B1); PG8_BAR; PG8_SCHED;
	s_add_i32 s4, 0, 0x18000
	s_add_i32 s5, 0, 0x1c000
	ds_read_b128 v[134:137], v238
	ds_read_b128 v[138:141], v238 offset:1024
	ds_read_b128 v[142:145], v238 offset:2048
	ds_read_b128 v[146:149], v238 offset:3072
	ds_read_b128 v[150:153], v239
	ds_read_b128 v[154:157], v239 offset:1024
	ds_read_b128 v[176:179], v239 offset:2048
	ds_read_b128 v[180:183], v239 offset:3072
	s_add_u32 s22, s54, 0x160000
	s_addc_u32 s23, s55, 0
	s_mov_b32 m0, s59
	ds_read_b128 v[184:187], v188 offset:32768
	ds_read_b128 v[190:193], v188 offset:33792
	ds_read_b128 v[212:215], v188 offset:34816
	ds_read_b128 v[216:219], v188 offset:35840
	ds_read_b128 v[220:223], v188 offset:36864
	ds_read_b128 v[224:227], v188 offset:37888
	ds_read_b128 v[228:231], v188 offset:38912
	global_load_lds_dwordx4 v2, s[22:23]
	s_mov_b32 m0, s60
	ds_read_b128 v[232:235], v188 offset:39936
	global_load_lds_dwordx4 v168, s[22:23]
	s_waitcnt vmcnt(8)
	s_waitcnt lgkmcnt(0)
	s_barrier
	v_mfma_f32_16x16x32_bf16 v[122:125], v[134:137], v[184:187], v[122:125]
	v_mfma_f32_16x16x32_bf16 v[122:125], v[138:141], v[190:193], v[122:125]
	v_mfma_f32_16x16x32_bf16 v[118:121], v[142:145], v[184:187], v[118:121]
	v_mfma_f32_16x16x32_bf16 v[118:121], v[146:149], v[190:193], v[118:121]
	v_mfma_f32_16x16x32_bf16 v[130:133], v[150:153], v[184:187], v[130:133]
	v_mfma_f32_16x16x32_bf16 v[130:133], v[154:157], v[190:193], v[130:133]
	v_mfma_f32_16x16x32_bf16 v[126:129], v[176:179], v[184:187], v[126:129]
	v_mfma_f32_16x16x32_bf16 v[126:129], v[180:183], v[190:193], v[126:129]
	v_mfma_f32_16x16x32_bf16 v[102:105], v[176:179], v[212:215], v[102:105]
	v_mfma_f32_16x16x32_bf16 v[102:105], v[180:183], v[216:219], v[102:105]
	v_mfma_f32_16x16x32_bf16 v[106:109], v[150:153], v[212:215], v[106:109]
	v_mfma_f32_16x16x32_bf16 v[106:109], v[154:157], v[216:219], v[106:109]
	v_mfma_f32_16x16x32_bf16 v[110:113], v[142:145], v[212:215], v[110:113]
	v_mfma_f32_16x16x32_bf16 v[110:113], v[146:149], v[216:219], v[110:113]
	v_mfma_f32_16x16x32_bf16 v[114:117], v[134:137], v[212:215], v[114:117]
	v_mfma_f32_16x16x32_bf16 v[114:117], v[138:141], v[216:219], v[114:117]
	v_mfma_f32_16x16x32_bf16 v[98:101], v[134:137], v[220:223], v[98:101]
	v_mfma_f32_16x16x32_bf16 v[98:101], v[138:141], v[224:227], v[98:101]
	v_mfma_f32_16x16x32_bf16 v[94:97], v[142:145], v[220:223], v[94:97]
	v_mfma_f32_16x16x32_bf16 v[94:97], v[146:149], v[224:227], v[94:97]
	v_mfma_f32_16x16x32_bf16 v[90:93], v[150:153], v[220:223], v[90:93]
	v_mfma_f32_16x16x32_bf16 v[90:93], v[154:157], v[224:227], v[90:93]
	v_mfma_f32_16x16x32_bf16 v[86:89], v[176:179], v[220:223], v[86:89]
	v_mfma_f32_16x16x32_bf16 v[86:89], v[180:183], v[224:227], v[86:89]
	v_mfma_f32_16x16x32_bf16 v[70:73], v[176:179], v[228:231], v[70:73]
	v_mfma_f32_16x16x32_bf16 v[70:73], v[180:183], v[232:235], v[70:73]
	v_mfma_f32_16x16x32_bf16 v[74:77], v[150:153], v[228:231], v[74:77]
	v_mfma_f32_16x16x32_bf16 v[74:77], v[154:157], v[232:235], v[74:77]
	v_mfma_f32_16x16x32_bf16 v[78:81], v[142:145], v[228:231], v[78:81]
	v_mfma_f32_16x16x32_bf16 v[78:81], v[146:149], v[232:235], v[78:81]
	v_mfma_f32_16x16x32_bf16 v[82:85], v[134:137], v[228:231], v[82:85]
	v_mfma_f32_16x16x32_bf16 v[82:85], v[138:141], v[232:235], v[82:85]
	s_barrier
	s_add_i32 s4, s4, s24
	s_add_i32 m0, s4, 0xffffff80
	ds_read_b128 v[184:187], v188 offset:49152
	ds_read_b128 v[190:193], v188 offset:50176
	ds_read_b128 v[212:215], v188 offset:51200
	ds_read_b128 v[216:219], v188 offset:52224
	global_load_lds_dwordx4 v4, s[52:53] offset:128
	s_add_i32 m0, s4, 0x1f80
	s_add_u32 s22, s52, 0x160080
	s_addc_u32 s23, s53, 0
	s_add_i32 s4, s5, s24
	global_load_lds_dwordx4 v170, s[52:53] offset:128
	s_mov_b32 m0, s4
	ds_read_b128 v[220:223], v188 offset:53248
	global_load_lds_dwordx4 v4, s[22:23]
	s_add_i32 m0, s4, 0x2000
	ds_read_b128 v[224:227], v188 offset:54272
	global_load_lds_dwordx4 v170, s[22:23]
	s_add_i32 m0, s61, 0xffffff80
	ds_read_b128 v[228:231], v188 offset:55296
	global_load_lds_dwordx4 v2, s[54:55] offset:128
	s_add_i32 m0, s64, 0xffffff80
	ds_read_b128 v[232:235], v188 offset:56320
	global_load_lds_dwordx4 v168, s[54:55] offset:128
	s_waitcnt vmcnt(8)
	s_waitcnt lgkmcnt(0)
	s_barrier
	v_mfma_f32_16x16x32_bf16 v[58:61], v[134:137], v[184:187], v[58:61]
	v_mfma_f32_16x16x32_bf16 v[58:61], v[138:141], v[190:193], v[58:61]
	v_mfma_f32_16x16x32_bf16 v[54:57], v[142:145], v[184:187], v[54:57]
	v_mfma_f32_16x16x32_bf16 v[54:57], v[146:149], v[190:193], v[54:57]
	v_mfma_f32_16x16x32_bf16 v[66:69], v[150:153], v[184:187], v[66:69]
	v_mfma_f32_16x16x32_bf16 v[66:69], v[154:157], v[190:193], v[66:69]
	v_mfma_f32_16x16x32_bf16 v[62:65], v[176:179], v[184:187], v[62:65]
	v_mfma_f32_16x16x32_bf16 v[62:65], v[180:183], v[190:193], v[62:65]
	v_mfma_f32_16x16x32_bf16 v[38:41], v[176:179], v[212:215], v[38:41]
	v_mfma_f32_16x16x32_bf16 v[38:41], v[180:183], v[216:219], v[38:41]
	v_mfma_f32_16x16x32_bf16 v[42:45], v[150:153], v[212:215], v[42:45]
	v_mfma_f32_16x16x32_bf16 v[42:45], v[154:157], v[216:219], v[42:45]
	v_mfma_f32_16x16x32_bf16 v[46:49], v[142:145], v[212:215], v[46:49]
	v_mfma_f32_16x16x32_bf16 v[46:49], v[146:149], v[216:219], v[46:49]
	v_mfma_f32_16x16x32_bf16 v[50:53], v[134:137], v[212:215], v[50:53]
	v_mfma_f32_16x16x32_bf16 v[50:53], v[138:141], v[216:219], v[50:53]
	v_mfma_f32_16x16x32_bf16 v[34:37], v[134:137], v[220:223], v[34:37]
	v_mfma_f32_16x16x32_bf16 v[34:37], v[138:141], v[224:227], v[34:37]
	v_mfma_f32_16x16x32_bf16 v[30:33], v[142:145], v[220:223], v[30:33]
	v_mfma_f32_16x16x32_bf16 v[30:33], v[146:149], v[224:227], v[30:33]
	v_mfma_f32_16x16x32_bf16 v[26:29], v[150:153], v[220:223], v[26:29]
	v_mfma_f32_16x16x32_bf16 v[26:29], v[154:157], v[224:227], v[26:29]
	v_mfma_f32_16x16x32_bf16 v[22:25], v[176:179], v[220:223], v[22:25]
	v_mfma_f32_16x16x32_bf16 v[22:25], v[180:183], v[224:227], v[22:25]
	v_mfma_f32_16x16x32_bf16 v[6:9], v[176:179], v[228:231], v[6:9]
	v_mfma_f32_16x16x32_bf16 v[6:9], v[180:183], v[232:235], v[6:9]
	v_mfma_f32_16x16x32_bf16 v[10:13], v[150:153], v[228:231], v[10:13]
	v_mfma_f32_16x16x32_bf16 v[10:13], v[154:157], v[232:235], v[10:13]
	v_mfma_f32_16x16x32_bf16 v[14:17], v[142:145], v[228:231], v[14:17]
	v_mfma_f32_16x16x32_bf16 v[14:17], v[146:149], v[232:235], v[14:17]
	v_mfma_f32_16x16x32_bf16 v[18:21], v[134:137], v[228:231], v[18:21]
	v_mfma_f32_16x16x32_bf16 v[18:21], v[138:141], v[232:235], v[18:21]
	s_barrier
	s_add_i32 s20, s20, 2
	s_add_u32 s33, s33, 0x100
	s_addc_u32 s69, s69, 0
	s_cmpk_gt_u32 s20, 0x55
	s_mov_b64 s[22:23], s[50:51]
	s_cbranch_scc0 .LBB0_299
	s_and_b64 vcc, exec, s[46:47]
	s_cbranch_vccz .LBB0_302
	s_barrier

; #define PG8_STAGE(bufoff, gbase, voff) do { _Pragma("unroll") for (int _i = 0; _i < 2; ++_i) \
;         __builtin_amdgcn_global_load_lds((const unsigned*)((const char*)(gbase) + (voff)[_i]), (PG8_LAS unsigned*)(lds + (bufoff) + ldsw + _i * 8192), 16, 0, 0); } while (0)
; #define PG8_LDA(dst, b, h) do { _Pragma("unroll") for (int m = 0; m < 4; ++m) _Pragma("unroll") for (int k = 0; k < 2; ++k) dst[m][k] = *(const PG8_LAS bf16x8*)(lds + PG8_SA(b, h) + aoff + m * 2048 + k * 1024); } while (0)
; #define PG8_LDB(dst, b, h) do { _Pragma("unroll") for (int n = 0; n < 2; ++n) _Pragma("unroll") for (int k = 0; k < 2; ++k) dst[n][k] = *(const PG8_LAS bf16x8*)(lds + PG8_SB(b, h) + boff + n * 2048 + k * 1024); } while (0)
; #define PG8_MMA(ai, bj, At, Bt) do { __builtin_amdgcn_s_setprio(1); _Pragma("unroll") for (int m = 0; m < 4; ++m) _Pragma("unroll") for (int n = 0; n < 2; ++n) _Pragma("unroll") for (int k = 0; k < 2; ++k) \
;         acc[ai][bj][m][n] = __builtin_amdgcn_mfma_f32_16x16x32_bf16(Bt[n][k], At[m][k], acc[ai][bj][m][n], 0, 0, 0); __builtin_amdgcn_s_setprio(0); } while (0)
; #define PG8_WAIT_V(n) asm volatile("s_waitcnt vmcnt(" #n ")" ::: "memory")
; #define PG8_WAIT_L(n) asm volatile("s_waitcnt lgkmcnt(" #n ")" ::: "memory")
; template <class Epi, class Sched, bool ALIGN_EPI = false, bool SP2 = false>
; __device__ __forceinline__ void gemm_phase(PG8_LAS unsigned char* lds, const Gemm g, const Sched& S, const Epi& E) {
;     ...
;             const bool last = (t == nt - 2);
;             const char* a1 = cA + (size_t)(t + 1) * kstep;
;             const char* a2 = last ? nA : cA + (size_t)(t + 2) * kstep; const char* b2 = last ? nB : cB + (size_t)(t + 2) * kstep;
;             const char* a3 = a2 + kstep; const char* b3 = b2 + kstep;
;             if (last && has_next) S.a_ready(nxt);
;             if constexpr (SP2) {
;             PG8_LDB(B0, 0, 0); PG8_LDB(B1, 0, 1); PG8_SCHED; PG8_LDA(At, 0, 0); PG8_STAGE(PG8_SA(1, 1), a1 + hstep, voffA);
;             PG8_WAIT_V(8); PG8_WAIT_L(0); PG8_BAR; PG8_MMA(0, 0, At, B0); PG8_MMA(0, 1, At, B1); PG8_BAR; PG8_SCHED;
;             PG8_LDA(At, 0, 1); PG8_STAGE(PG8_SB(0, 0), b2, voffB); PG8_STAGE(PG8_SB(0, 1), b2 + hstep, voffB); PG8_STAGE(PG8_SA(0, 0), a2, voffA);
;             PG8_WAIT_V(8); PG8_WAIT_L(0); PG8_BAR; PG8_MMA(1, 0, At, B0); PG8_MMA(1, 1, At, B1); PG8_BAR; PG8_SCHED;
.LBB0_387:
	ds_read_b128 v[144:147], v156
	ds_read_b128 v[148:151], v156 offset:1024
	ds_read_b128 v[168:171], v156 offset:2048
	ds_read_b128 v[172:175], v156 offset:3072
	ds_read_b128 v[176:179], v157
	ds_read_b128 v[180:183], v157 offset:1024
	ds_read_b128 v[184:187], v157 offset:2048
	ds_read_b128 v[188:191], v157 offset:3072
	ds_read_b128 v[212:215], v155
	ds_read_b128 v[216:219], v155 offset:1024
	ds_read_b128 v[220:223], v155 offset:2048
	ds_read_b128 v[224:227], v155 offset:3072
	ds_read_b128 v[228:231], v155 offset:4096
	ds_read_b128 v[232:235], v155 offset:5120
	ds_read_b128 v[236:239], v155 offset:6144
	ds_read_b128 v[240:243], v155 offset:7168
	s_add_i32 m0, s60, 0xc000
	s_add_u32 s4, s56, 0xfff80080
	s_addc_u32 s5, s57, -1
	global_load_lds_dwordx4 v140, s[56:57]
	s_add_i32 m0, s60, 0xe000
	s_add_i32 s6, 0, 0x10000
	global_load_lds_dwordx4 v142, s[56:57]
	s_cmp_eq_u32 s20, 28
	s_cselect_b32 s59, s47, s5
	s_cselect_b32 s58, s75, s4
	s_cselect_b32 s55, s49, s77
	s_cselect_b32 s54, vcc_lo, s71
	s_add_i32 s4, 0, 0x14000
	s_waitcnt vmcnt(8)
	s_waitcnt lgkmcnt(0)
	s_barrier
	v_mfma_f32_16x16x32_bf16 v[122:125], v[144:147], v[212:215], v[122:125]
	v_mfma_f32_16x16x32_bf16 v[122:125], v[148:151], v[216:219], v[122:125]
	v_mfma_f32_16x16x32_bf16 v[118:121], v[168:171], v[212:215], v[118:121]
	v_mfma_f32_16x16x32_bf16 v[118:121], v[172:175], v[216:219], v[118:121]
	v_mfma_f32_16x16x32_bf16 v[130:133], v[176:179], v[212:215], v[130:133]
	v_mfma_f32_16x16x32_bf16 v[130:133], v[180:183], v[216:219], v[130:133]
	v_mfma_f32_16x16x32_bf16 v[126:129], v[184:187], v[212:215], v[126:129]
	v_mfma_f32_16x16x32_bf16 v[126:129], v[188:191], v[216:219], v[126:129]
	v_mfma_f32_16x16x32_bf16 v[110:113], v[184:187], v[220:223], v[110:113]
	v_mfma_f32_16x16x32_bf16 v[110:113], v[188:191], v[224:227], v[110:113]
	v_mfma_f32_16x16x32_bf16 v[114:117], v[176:179], v[220:223], v[114:117]
	v_mfma_f32_16x16x32_bf16 v[114:117], v[180:183], v[224:227], v[114:117]
	v_mfma_f32_16x16x32_bf16 v[102:105], v[168:171], v[220:223], v[102:105]
	v_mfma_f32_16x16x32_bf16 v[102:105], v[172:175], v[224:227], v[102:105]
	v_mfma_f32_16x16x32_bf16 v[106:109], v[144:147], v[220:223], v[106:109]
	v_mfma_f32_16x16x32_bf16 v[106:109], v[148:151], v[224:227], v[106:109]
	v_mfma_f32_16x16x32_bf16 v[90:93], v[144:147], v[228:231], v[90:93]
	v_mfma_f32_16x16x32_bf16 v[90:93], v[148:151], v[232:235], v[90:93]
	v_mfma_f32_16x16x32_bf16 v[86:89], v[168:171], v[228:231], v[86:89]
	v_mfma_f32_16x16x32_bf16 v[86:89], v[172:175], v[232:235], v[86:89]
	v_mfma_f32_16x16x32_bf16 v[98:101], v[176:179], v[228:231], v[98:101]
	v_mfma_f32_16x16x32_bf16 v[98:101], v[180:183], v[232:235], v[98:101]
	v_mfma_f32_16x16x32_bf16 v[94:97], v[184:187], v[228:231], v[94:97]
	v_mfma_f32_16x16x32_bf16 v[94:97], v[188:191], v[232:235], v[94:97]
	v_mfma_f32_16x16x32_bf16 v[78:81], v[184:187], v[236:239], v[78:81]
	v_mfma_f32_16x16x32_bf16 v[78:81], v[188:191], v[240:243], v[78:81]
	v_mfma_f32_16x16x32_bf16 v[82:85], v[176:179], v[236:239], v[82:85]
	v_mfma_f32_16x16x32_bf16 v[82:85], v[180:183], v[240:243], v[82:85]
	v_mfma_f32_16x16x32_bf16 v[70:73], v[168:171], v[236:239], v[70:73]
	v_mfma_f32_16x16x32_bf16 v[70:73], v[172:175], v[240:243], v[70:73]
	v_mfma_f32_16x16x32_bf16 v[74:77], v[144:147], v[236:239], v[74:77]
	v_mfma_f32_16x16x32_bf16 v[74:77], v[148:151], v[240:243], v[74:77]
	s_barrier
	ds_read_b128 v[212:215], v155 offset:16384
	ds_read_b128 v[216:219], v155 offset:17408
	ds_read_b128 v[220:223], v155 offset:18432
	ds_read_b128 v[224:227], v155 offset:19456
	s_add_i32 s5, s6, s24
	s_mov_b32 m0, s5
	s_add_u32 s34, s54, 0x80000
	s_addc_u32 s35, s55, 0
	global_load_lds_dwordx4 v4, s[54:55]
	s_add_i32 m0, s5, 0x2000
	s_add_i32 s4, s4, s24
	global_load_lds_dwordx4 v2, s[54:55]
	s_mov_b32 m0, s4
	ds_read_b128 v[228:231], v155 offset:20480
	global_load_lds_dwordx4 v4, s[34:35]
	s_add_i32 m0, s4, 0x2000
	ds_read_b128 v[232:235], v155 offset:21504
	global_load_lds_dwordx4 v2, s[34:35]
	s_mov_b32 m0, s60
	ds_read_b128 v[236:239], v155 offset:22528
	global_load_lds_dwordx4 v136, s[58:59]
	s_mov_b32 m0, s61
	ds_read_b128 v[240:243], v155 offset:23552
	global_load_lds_dwordx4 v134, s[58:59]
	s_waitcnt vmcnt(8)
	s_waitcnt lgkmcnt(0)
	s_barrier
	v_mfma_f32_16x16x32_bf16 v[58:61], v[144:147], v[212:215], v[58:61]
	v_mfma_f32_16x16x32_bf16 v[58:61], v[148:151], v[216:219], v[58:61]
	v_mfma_f32_16x16x32_bf16 v[54:57], v[168:171], v[212:215], v[54:57]
	v_mfma_f32_16x16x32_bf16 v[54:57], v[172:175], v[216:219], v[54:57]
	v_mfma_f32_16x16x32_bf16 v[66:69], v[176:179], v[212:215], v[66:69]
	v_mfma_f32_16x16x32_bf16 v[66:69], v[180:183], v[216:219], v[66:69]
	v_mfma_f32_16x16x32_bf16 v[62:65], v[184:187], v[212:215], v[62:65]
	v_mfma_f32_16x16x32_bf16 v[62:65], v[188:191], v[216:219], v[62:65]
	v_mfma_f32_16x16x32_bf16 v[46:49], v[184:187], v[220:223], v[46:49]
	v_mfma_f32_16x16x32_bf16 v[46:49], v[188:191], v[224:227], v[46:49]
	v_mfma_f32_16x16x32_bf16 v[50:53], v[176:179], v[220:223], v[50:53]
	v_mfma_f32_16x16x32_bf16 v[50:53], v[180:183], v[224:227], v[50:53]
	v_mfma_f32_16x16x32_bf16 v[38:41], v[168:171], v[220:223], v[38:41]
	v_mfma_f32_16x16x32_bf16 v[38:41], v[172:175], v[224:227], v[38:41]
	v_mfma_f32_16x16x32_bf16 v[42:45], v[144:147], v[220:223], v[42:45]
	v_mfma_f32_16x16x32_bf16 v[42:45], v[148:151], v[224:227], v[42:45]
	v_mfma_f32_16x16x32_bf16 v[26:29], v[144:147], v[228:231], v[26:29]
	v_mfma_f32_16x16x32_bf16 v[26:29], v[148:151], v[232:235], v[26:29]
	v_mfma_f32_16x16x32_bf16 v[22:25], v[168:171], v[228:231], v[22:25]
	v_mfma_f32_16x16x32_bf16 v[22:25], v[172:175], v[232:235], v[22:25]
	v_mfma_f32_16x16x32_bf16 v[34:37], v[176:179], v[228:231], v[34:37]
	v_mfma_f32_16x16x32_bf16 v[34:37], v[180:183], v[232:235], v[34:37]
	v_mfma_f32_16x16x32_bf16 v[30:33], v[184:187], v[228:231], v[30:33]
	v_mfma_f32_16x16x32_bf16 v[30:33], v[188:191], v[232:235], v[30:33]
	v_mfma_f32_16x16x32_bf16 v[18:21], v[184:187], v[236:239], v[18:21]
	v_mfma_f32_16x16x32_bf16 v[18:21], v[188:191], v[240:243], v[18:21]
	v_mfma_f32_16x16x32_bf16 v[14:17], v[176:179], v[236:239], v[14:17]
	v_mfma_f32_16x16x32_bf16 v[14:17], v[180:183], v[240:243], v[14:17]
	v_mfma_f32_16x16x32_bf16 v[6:9], v[168:171], v[236:239], v[6:9]
	v_mfma_f32_16x16x32_bf16 v[6:9], v[172:175], v[240:243], v[6:9]
	v_mfma_f32_16x16x32_bf16 v[10:13], v[144:147], v[236:239], v[10:13]
	v_mfma_f32_16x16x32_bf16 v[10:13], v[148:151], v[240:243], v[10:13]
	s_barrier
; #define PG8_STAGE(bufoff, gbase, voff) do { _Pragma("unroll") for (int _i = 0; _i < 2; ++_i) \
;         __builtin_amdgcn_global_load_lds((const unsigned*)((const char*)(gbase) + (voff)[_i]), (PG8_LAS unsigned*)(lds + (bufoff) + ldsw + _i * 8192), 16, 0, 0); } while (0)
; #define PG8_LDA(dst, b, h) do { _Pragma("unroll") for (int m = 0; m < 4; ++m) _Pragma("unroll") for (int k = 0; k < 2; ++k) dst[m][k] = *(const PG8_LAS bf16x8*)(lds + PG8_SA(b, h) + aoff + m * 2048 + k * 1024); } while (0)
; #define PG8_LDB(dst, b, h) do { _Pragma("unroll") for (int n = 0; n < 2; ++n) _Pragma("unroll") for (int k = 0; k < 2; ++k) dst[n][k] = *(const PG8_LAS bf16x8*)(lds + PG8_SB(b, h) + boff + n * 2048 + k * 1024); } while (0)
; #define PG8_MMA(ai, bj, At, Bt) do { __builtin_amdgcn_s_setprio(1); _Pragma("unroll") for (int m = 0; m < 4; ++m) _Pragma("unroll") for (int n = 0; n < 2; ++n) _Pragma("unroll") for (int k = 0; k < 2; ++k) \
;         acc[ai][bj][m][n] = __builtin_amdgcn_mfma_f32_16x16x32_bf16(Bt[n][k], At[m][k], acc[ai][bj][m][n], 0, 0, 0); __builtin_amdgcn_s_setprio(0); } while (0)
; #define PG8_WAIT_V(n) asm volatile("s_waitcnt vmcnt(" #n ")" ::: "memory")
; #define PG8_WAIT_L(n) asm volatile("s_waitcnt lgkmcnt(" #n ")" ::: "memory")
; #define PG8_BAR __builtin_amdgcn_s_barrier()
; #define PG8_SCHED __builtin_amdgcn_sched_barrier(0)
; template <class Epi, class Sched, bool ALIGN_EPI = false, bool SP2 = false>
; __device__ __forceinline__ void gemm_phase(PG8_LAS unsigned char* lds, const Gemm g, const Sched& S, const Epi& E) {
;     ...
;         for (int t = 0; t < nt; t += 2) {
;             const bool last = (t == nt - 2);
;             const char* a1 = cA + (size_t)(t + 1) * kstep;
;             const char* a2 = last ? nA : cA + (size_t)(t + 2) * kstep; const char* b2 = last ? nB : cB + (size_t)(t + 2) * kstep;
;     ...
;             PG8_LDB(B0, 1, 0); PG8_LDB(B1, 1, 1); PG8_SCHED; PG8_LDA(At, 1, 0); PG8_STAGE(PG8_SA(0, 1), a2 + hstep, voffA);
;             PG8_WAIT_V(8); PG8_WAIT_L(0); PG8_BAR; PG8_MMA(0, 0, At, B0); PG8_MMA(0, 1, At, B1); PG8_BAR; PG8_SCHED;
;             PG8_LDA(At, 1, 1); PG8_STAGE(PG8_SB(1, 0), b3, voffB); PG8_STAGE(PG8_SB(1, 1), b3 + hstep, voffB); PG8_STAGE(PG8_SA(1, 0), a3, voffA);
;             PG8_WAIT_V(8); PG8_WAIT_L(0); PG8_BAR; PG8_MMA(1, 0, At, B0); PG8_MMA(1, 1, At, B1); PG8_BAR; PG8_SCHED;
	ds_read_b128 v[144:147], v192
	ds_read_b128 v[148:151], v192 offset:1024
	ds_read_b128 v[168:171], v192 offset:2048
	ds_read_b128 v[172:175], v192 offset:3072
	ds_read_b128 v[176:179], v193
	ds_read_b128 v[180:183], v193 offset:1024
	ds_read_b128 v[184:187], v193 offset:2048
	ds_read_b128 v[188:191], v193 offset:3072
	ds_read_b128 v[212:215], v155 offset:32768
	ds_read_b128 v[216:219], v155 offset:33792
	ds_read_b128 v[220:223], v155 offset:34816
	ds_read_b128 v[224:227], v155 offset:35840
	ds_read_b128 v[228:231], v155 offset:36864
	ds_read_b128 v[232:235], v155 offset:37888
	ds_read_b128 v[236:239], v155 offset:38912
	ds_read_b128 v[240:243], v155 offset:39936
	s_add_u32 s34, s58, 0x80000
	s_addc_u32 s35, s59, 0
	s_mov_b32 m0, s64
	s_add_i32 s4, 0, 0x18000
	global_load_lds_dwordx4 v136, s[34:35]
	s_mov_b32 m0, s65
	s_add_i32 s5, 0, 0x1c000
	global_load_lds_dwordx4 v134, s[34:35]
	s_waitcnt vmcnt(8)
	s_waitcnt lgkmcnt(0)
	s_barrier
	v_mfma_f32_16x16x32_bf16 v[122:125], v[144:147], v[212:215], v[122:125]
	v_mfma_f32_16x16x32_bf16 v[122:125], v[148:151], v[216:219], v[122:125]
	v_mfma_f32_16x16x32_bf16 v[118:121], v[168:171], v[212:215], v[118:121]
	v_mfma_f32_16x16x32_bf16 v[118:121], v[172:175], v[216:219], v[118:121]
	v_mfma_f32_16x16x32_bf16 v[130:133], v[176:179], v[212:215], v[130:133]
	v_mfma_f32_16x16x32_bf16 v[130:133], v[180:183], v[216:219], v[130:133]
	v_mfma_f32_16x16x32_bf16 v[126:129], v[184:187], v[212:215], v[126:129]
	v_mfma_f32_16x16x32_bf16 v[126:129], v[188:191], v[216:219], v[126:129]
	v_mfma_f32_16x16x32_bf16 v[110:113], v[184:187], v[220:223], v[110:113]
	v_mfma_f32_16x16x32_bf16 v[110:113], v[188:191], v[224:227], v[110:113]
	v_mfma_f32_16x16x32_bf16 v[114:117], v[176:179], v[220:223], v[114:117]
	v_mfma_f32_16x16x32_bf16 v[114:117], v[180:183], v[224:227], v[114:117]
	v_mfma_f32_16x16x32_bf16 v[102:105], v[168:171], v[220:223], v[102:105]
	v_mfma_f32_16x16x32_bf16 v[102:105], v[172:175], v[224:227], v[102:105]
	v_mfma_f32_16x16x32_bf16 v[106:109], v[144:147], v[220:223], v[106:109]
	v_mfma_f32_16x16x32_bf16 v[106:109], v[148:151], v[224:227], v[106:109]
	v_mfma_f32_16x16x32_bf16 v[90:93], v[144:147], v[228:231], v[90:93]
	v_mfma_f32_16x16x32_bf16 v[90:93], v[148:151], v[232:235], v[90:93]
	v_mfma_f32_16x16x32_bf16 v[86:89], v[168:171], v[228:231], v[86:89]
	v_mfma_f32_16x16x32_bf16 v[86:89], v[172:175], v[232:235], v[86:89]
	v_mfma_f32_16x16x32_bf16 v[98:101], v[176:179], v[228:231], v[98:101]
	v_mfma_f32_16x16x32_bf16 v[98:101], v[180:183], v[232:235], v[98:101]
	v_mfma_f32_16x16x32_bf16 v[94:97], v[184:187], v[228:231], v[94:97]
	v_mfma_f32_16x16x32_bf16 v[94:97], v[188:191], v[232:235], v[94:97]
	v_mfma_f32_16x16x32_bf16 v[78:81], v[184:187], v[236:239], v[78:81]
	v_mfma_f32_16x16x32_bf16 v[78:81], v[188:191], v[240:243], v[78:81]
	v_mfma_f32_16x16x32_bf16 v[82:85], v[176:179], v[236:239], v[82:85]
	v_mfma_f32_16x16x32_bf16 v[82:85], v[180:183], v[240:243], v[82:85]
	v_mfma_f32_16x16x32_bf16 v[70:73], v[168:171], v[236:239], v[70:73]
	v_mfma_f32_16x16x32_bf16 v[70:73], v[172:175], v[240:243], v[70:73]
	v_mfma_f32_16x16x32_bf16 v[74:77], v[144:147], v[236:239], v[74:77]
	v_mfma_f32_16x16x32_bf16 v[74:77], v[148:151], v[240:243], v[74:77]
	s_barrier
	ds_read_b128 v[212:215], v155 offset:49152
	ds_read_b128 v[216:219], v155 offset:50176
	ds_read_b128 v[220:223], v155 offset:51200
	s_add_i32 s4, s4, s24
	s_add_i32 m0, s4, 0xffffff80
	ds_read_b128 v[224:227], v155 offset:52224
	global_load_lds_dwordx4 v4, s[54:55] offset:128
	s_add_i32 m0, s4, 0x1f80
	s_add_i32 s4, s5, s24
	global_load_lds_dwordx4 v2, s[54:55] offset:128
	s_add_u32 s34, s54, 0x80080
	s_addc_u32 s35, s55, 0
	s_mov_b32 m0, s4
	ds_read_b128 v[228:231], v155 offset:53248
	global_load_lds_dwordx4 v4, s[34:35]
	s_add_i32 m0, s4, 0x2000
	ds_read_b128 v[232:235], v155 offset:54272
	global_load_lds_dwordx4 v2, s[34:35]
	s_add_i32 m0, s67, 0xffffff80
	ds_read_b128 v[236:239], v155 offset:55296
	global_load_lds_dwordx4 v136, s[58:59] offset:128
	s_add_i32 m0, s72, 0xffffff80
	ds_read_b128 v[240:243], v155 offset:56320
	global_load_lds_dwordx4 v134, s[58:59] offset:128
	s_waitcnt vmcnt(8)
	s_waitcnt lgkmcnt(0)
	s_barrier
	v_mfma_f32_16x16x32_bf16 v[58:61], v[144:147], v[212:215], v[58:61]
	v_mfma_f32_16x16x32_bf16 v[58:61], v[148:151], v[216:219], v[58:61]
	v_mfma_f32_16x16x32_bf16 v[54:57], v[168:171], v[212:215], v[54:57]
	v_mfma_f32_16x16x32_bf16 v[54:57], v[172:175], v[216:219], v[54:57]
	v_mfma_f32_16x16x32_bf16 v[66:69], v[176:179], v[212:215], v[66:69]
	v_mfma_f32_16x16x32_bf16 v[66:69], v[180:183], v[216:219], v[66:69]
	v_mfma_f32_16x16x32_bf16 v[62:65], v[184:187], v[212:215], v[62:65]
	v_mfma_f32_16x16x32_bf16 v[62:65], v[188:191], v[216:219], v[62:65]
	v_mfma_f32_16x16x32_bf16 v[46:49], v[184:187], v[220:223], v[46:49]
	v_mfma_f32_16x16x32_bf16 v[46:49], v[188:191], v[224:227], v[46:49]
	v_mfma_f32_16x16x32_bf16 v[50:53], v[176:179], v[220:223], v[50:53]
	v_mfma_f32_16x16x32_bf16 v[50:53], v[180:183], v[224:227], v[50:53]
	v_mfma_f32_16x16x32_bf16 v[38:41], v[168:171], v[220:223], v[38:41]
	v_mfma_f32_16x16x32_bf16 v[38:41], v[172:175], v[224:227], v[38:41]
	v_mfma_f32_16x16x32_bf16 v[42:45], v[144:147], v[220:223], v[42:45]
	v_mfma_f32_16x16x32_bf16 v[42:45], v[148:151], v[224:227], v[42:45]
	v_mfma_f32_16x16x32_bf16 v[26:29], v[144:147], v[228:231], v[26:29]
	v_mfma_f32_16x16x32_bf16 v[26:29], v[148:151], v[232:235], v[26:29]
	v_mfma_f32_16x16x32_bf16 v[22:25], v[168:171], v[228:231], v[22:25]
	v_mfma_f32_16x16x32_bf16 v[22:25], v[172:175], v[232:235], v[22:25]
	v_mfma_f32_16x16x32_bf16 v[34:37], v[176:179], v[228:231], v[34:37]
	v_mfma_f32_16x16x32_bf16 v[34:37], v[180:183], v[232:235], v[34:37]
	v_mfma_f32_16x16x32_bf16 v[30:33], v[184:187], v[228:231], v[30:33]
	v_mfma_f32_16x16x32_bf16 v[30:33], v[188:191], v[232:235], v[30:33]
	v_mfma_f32_16x16x32_bf16 v[18:21], v[184:187], v[236:239], v[18:21]
	v_mfma_f32_16x16x32_bf16 v[18:21], v[188:191], v[240:243], v[18:21]
	v_mfma_f32_16x16x32_bf16 v[14:17], v[176:179], v[236:239], v[14:17]
	v_mfma_f32_16x16x32_bf16 v[14:17], v[180:183], v[240:243], v[14:17]
	v_mfma_f32_16x16x32_bf16 v[6:9], v[168:171], v[236:239], v[6:9]
	v_mfma_f32_16x16x32_bf16 v[6:9], v[172:175], v[240:243], v[6:9]
	v_mfma_f32_16x16x32_bf16 v[10:13], v[144:147], v[236:239], v[10:13]
	v_mfma_f32_16x16x32_bf16 v[10:13], v[148:151], v[240:243], v[10:13]
	s_barrier
	s_add_i32 s20, s20, 2
	s_add_u32 s56, s56, 0x100
	s_addc_u32 s57, s57, 0
	s_add_u32 s71, s71, 0x100
	s_addc_u32 s77, s77, 0
	s_cmp_gt_u32 s20, 29
	s_cbranch_scc0 .LBB0_387
	s_and_b64 vcc, exec, s[44:45]
	s_movk_i32 s75, 0x800
	s_movk_i32 s77, 0x6000
	s_mov_b32 s71, 0x44800000
	s_cbranch_vccz .LBB0_390
	s_barrier

; #define PG8_STAGE(bufoff, gbase, voff) do { _Pragma("unroll") for (int _i = 0; _i < 2; ++_i) \
;         __builtin_amdgcn_global_load_lds((const unsigned*)((const char*)(gbase) + (voff)[_i]), (PG8_LAS unsigned*)(lds + (bufoff) + ldsw + _i * 8192), 16, 0, 0); } while (0)
; #define PG8_LDA(dst, b, h) do { _Pragma("unroll") for (int m = 0; m < 4; ++m) _Pragma("unroll") for (int k = 0; k < 2; ++k) dst[m][k] = *(const PG8_LAS bf16x8*)(lds + PG8_SA(b, h) + aoff + m * 2048 + k * 1024); } while (0)
; #define PG8_LDB(dst, b, h) do { _Pragma("unroll") for (int n = 0; n < 2; ++n) _Pragma("unroll") for (int k = 0; k < 2; ++k) dst[n][k] = *(const PG8_LAS bf16x8*)(lds + PG8_SB(b, h) + boff + n * 2048 + k * 1024); } while (0)
; #define PG8_MMA(ai, bj, At, Bt) do { __builtin_amdgcn_s_setprio(1); _Pragma("unroll") for (int m = 0; m < 4; ++m) _Pragma("unroll") for (int n = 0; n < 2; ++n) _Pragma("unroll") for (int k = 0; k < 2; ++k) \
;         acc[ai][bj][m][n] = __builtin_amdgcn_mfma_f32_16x16x32_bf16(Bt[n][k], At[m][k], acc[ai][bj][m][n], 0, 0, 0); __builtin_amdgcn_s_setprio(0); } while (0)
; #define PG8_WAIT_V(n) asm volatile("s_waitcnt vmcnt(" #n ")" ::: "memory")
; #define PG8_WAIT_L(n) asm volatile("s_waitcnt lgkmcnt(" #n ")" ::: "memory")
; template <class Epi, class Sched, bool ALIGN_EPI = false, bool SP2 = false>
; __device__ __forceinline__ void gemm_phase(PG8_LAS unsigned char* lds, const Gemm g, const Sched& S, const Epi& E) {
;     ...
;             const bool last = (t == nt - 2);
;             const char* a1 = cA + (size_t)(t + 1) * kstep;
;             const char* a2 = last ? nA : cA + (size_t)(t + 2) * kstep; const char* b2 = last ? nB : cB + (size_t)(t + 2) * kstep;
;             const char* a3 = a2 + kstep; const char* b3 = b2 + kstep;
;             if (last && has_next) S.a_ready(nxt);
;             if constexpr (SP2) {
;             PG8_LDB(B0, 0, 0); PG8_LDB(B1, 0, 1); PG8_SCHED; PG8_LDA(At, 0, 0); PG8_STAGE(PG8_SA(1, 1), a1 + hstep, voffA);
;             PG8_WAIT_V(8); PG8_WAIT_L(0); PG8_BAR; PG8_MMA(0, 0, At, B0); PG8_MMA(0, 1, At, B1); PG8_BAR; PG8_SCHED;
;             PG8_LDA(At, 0, 1); PG8_STAGE(PG8_SB(0, 0), b2, voffB); PG8_STAGE(PG8_SB(0, 1), b2 + hstep, voffB); PG8_STAGE(PG8_SA(0, 0), a2, voffA);
;             PG8_WAIT_V(8); PG8_WAIT_L(0); PG8_BAR; PG8_MMA(1, 0, At, B0); PG8_MMA(1, 1, At, B1); PG8_BAR; PG8_SCHED;
.LBB0_1738:
	s_add_u32 s4, s50, 0xfff80080
	s_addc_u32 s5, s51, -1
	s_add_i32 s6, 0, 0x10000
	s_cmp_eq_u32 s20, 28
	s_cselect_b32 s53, s43, s5
	s_cselect_b32 s52, s66, s4
	s_cselect_b32 s49, s45, s71
	s_cselect_b32 s48, s67, s69
	s_add_i32 s4, 0, 0x14000
	ds_read_b128 v[134:137], v234
	ds_read_b128 v[138:141], v234 offset:1024
	ds_read_b128 v[142:145], v234 offset:2048
	ds_read_b128 v[146:149], v234 offset:3072
	ds_read_b128 v[150:153], v235
	ds_read_b128 v[154:157], v235 offset:1024
	ds_read_b128 v[176:179], v235 offset:2048
	ds_read_b128 v[180:183], v235 offset:3072
	s_add_i32 m0, s54, 0xc000
	ds_read_b128 v[184:187], v188
	ds_read_b128 v[190:193], v188 offset:1024
	ds_read_b128 v[210:213], v188 offset:2048
	ds_read_b128 v[214:217], v188 offset:3072
	ds_read_b128 v[218:221], v188 offset:4096
	ds_read_b128 v[222:225], v188 offset:5120
	ds_read_b128 v[226:229], v188 offset:6144
	global_load_lds_dwordx4 v172, s[50:51]
	s_add_i32 m0, s54, 0xe000
	ds_read_b128 v[230:233], v188 offset:7168
	global_load_lds_dwordx4 v174, s[50:51]
	s_waitcnt vmcnt(8)
	s_waitcnt lgkmcnt(0)
	s_barrier
	v_mfma_f32_16x16x32_bf16 v[122:125], v[134:137], v[184:187], v[122:125]
	v_mfma_f32_16x16x32_bf16 v[122:125], v[138:141], v[190:193], v[122:125]
	v_mfma_f32_16x16x32_bf16 v[118:121], v[142:145], v[184:187], v[118:121]
	v_mfma_f32_16x16x32_bf16 v[118:121], v[146:149], v[190:193], v[118:121]
	v_mfma_f32_16x16x32_bf16 v[130:133], v[150:153], v[184:187], v[130:133]
	v_mfma_f32_16x16x32_bf16 v[130:133], v[154:157], v[190:193], v[130:133]
	v_mfma_f32_16x16x32_bf16 v[126:129], v[176:179], v[184:187], v[126:129]
	v_mfma_f32_16x16x32_bf16 v[126:129], v[180:183], v[190:193], v[126:129]
	v_mfma_f32_16x16x32_bf16 v[102:105], v[176:179], v[210:213], v[102:105]
	v_mfma_f32_16x16x32_bf16 v[102:105], v[180:183], v[214:217], v[102:105]
	v_mfma_f32_16x16x32_bf16 v[110:113], v[150:153], v[210:213], v[110:113]
	v_mfma_f32_16x16x32_bf16 v[110:113], v[154:157], v[214:217], v[110:113]
	v_mfma_f32_16x16x32_bf16 v[106:109], v[142:145], v[210:213], v[106:109]
	v_mfma_f32_16x16x32_bf16 v[106:109], v[146:149], v[214:217], v[106:109]
	v_mfma_f32_16x16x32_bf16 v[114:117], v[134:137], v[210:213], v[114:117]
	v_mfma_f32_16x16x32_bf16 v[114:117], v[138:141], v[214:217], v[114:117]
	v_mfma_f32_16x16x32_bf16 v[98:101], v[134:137], v[218:221], v[98:101]
	v_mfma_f32_16x16x32_bf16 v[98:101], v[138:141], v[222:225], v[98:101]
	v_mfma_f32_16x16x32_bf16 v[90:93], v[142:145], v[218:221], v[90:93]
	v_mfma_f32_16x16x32_bf16 v[90:93], v[146:149], v[222:225], v[90:93]
	v_mfma_f32_16x16x32_bf16 v[94:97], v[150:153], v[218:221], v[94:97]
	v_mfma_f32_16x16x32_bf16 v[94:97], v[154:157], v[222:225], v[94:97]
	v_mfma_f32_16x16x32_bf16 v[86:89], v[176:179], v[218:221], v[86:89]
	v_mfma_f32_16x16x32_bf16 v[86:89], v[180:183], v[222:225], v[86:89]
	v_mfma_f32_16x16x32_bf16 v[70:73], v[176:179], v[226:229], v[70:73]
	v_mfma_f32_16x16x32_bf16 v[70:73], v[180:183], v[230:233], v[70:73]
	v_mfma_f32_16x16x32_bf16 v[78:81], v[150:153], v[226:229], v[78:81]
	v_mfma_f32_16x16x32_bf16 v[78:81], v[154:157], v[230:233], v[78:81]
	v_mfma_f32_16x16x32_bf16 v[74:77], v[142:145], v[226:229], v[74:77]
	v_mfma_f32_16x16x32_bf16 v[74:77], v[146:149], v[230:233], v[74:77]
	v_mfma_f32_16x16x32_bf16 v[82:85], v[134:137], v[226:229], v[82:85]
	v_mfma_f32_16x16x32_bf16 v[82:85], v[138:141], v[230:233], v[82:85]
	s_barrier
	s_add_i32 s5, s6, s24
	s_mov_b32 m0, s5
	ds_read_b128 v[184:187], v188 offset:16384
	ds_read_b128 v[190:193], v188 offset:17408
	ds_read_b128 v[210:213], v188 offset:18432
	ds_read_b128 v[214:217], v188 offset:19456
	global_load_lds_dwordx4 v4, s[48:49]
	s_add_i32 m0, s5, 0x2000
	s_add_u32 s34, s48, 0x80000
	s_addc_u32 s35, s49, 0
	s_add_i32 s4, s4, s24
	global_load_lds_dwordx4 v2, s[48:49]
	s_mov_b32 m0, s4
	ds_read_b128 v[218:221], v188 offset:20480
	global_load_lds_dwordx4 v4, s[34:35]
	s_add_i32 m0, s4, 0x2000
	ds_read_b128 v[222:225], v188 offset:21504
	global_load_lds_dwordx4 v2, s[34:35]
	s_mov_b32 m0, s54
	ds_read_b128 v[226:229], v188 offset:22528
	global_load_lds_dwordx4 v170, s[52:53]
	s_mov_b32 m0, s55
	ds_read_b128 v[230:233], v188 offset:23552
	global_load_lds_dwordx4 v168, s[52:53]
	s_waitcnt vmcnt(8)
	s_waitcnt lgkmcnt(0)
	s_barrier
	v_mfma_f32_16x16x32_bf16 v[58:61], v[134:137], v[184:187], v[58:61]
	v_mfma_f32_16x16x32_bf16 v[58:61], v[138:141], v[190:193], v[58:61]
	v_mfma_f32_16x16x32_bf16 v[54:57], v[142:145], v[184:187], v[54:57]
	v_mfma_f32_16x16x32_bf16 v[54:57], v[146:149], v[190:193], v[54:57]
	v_mfma_f32_16x16x32_bf16 v[66:69], v[150:153], v[184:187], v[66:69]
	v_mfma_f32_16x16x32_bf16 v[66:69], v[154:157], v[190:193], v[66:69]
	v_mfma_f32_16x16x32_bf16 v[62:65], v[176:179], v[184:187], v[62:65]
	v_mfma_f32_16x16x32_bf16 v[62:65], v[180:183], v[190:193], v[62:65]
	v_mfma_f32_16x16x32_bf16 v[38:41], v[176:179], v[210:213], v[38:41]
	v_mfma_f32_16x16x32_bf16 v[38:41], v[180:183], v[214:217], v[38:41]
	v_mfma_f32_16x16x32_bf16 v[46:49], v[150:153], v[210:213], v[46:49]
	v_mfma_f32_16x16x32_bf16 v[46:49], v[154:157], v[214:217], v[46:49]
	v_mfma_f32_16x16x32_bf16 v[42:45], v[142:145], v[210:213], v[42:45]
	v_mfma_f32_16x16x32_bf16 v[42:45], v[146:149], v[214:217], v[42:45]
	v_mfma_f32_16x16x32_bf16 v[50:53], v[134:137], v[210:213], v[50:53]
	v_mfma_f32_16x16x32_bf16 v[50:53], v[138:141], v[214:217], v[50:53]
	v_mfma_f32_16x16x32_bf16 v[34:37], v[134:137], v[218:221], v[34:37]
	v_mfma_f32_16x16x32_bf16 v[34:37], v[138:141], v[222:225], v[34:37]
	v_mfma_f32_16x16x32_bf16 v[26:29], v[142:145], v[218:221], v[26:29]
	v_mfma_f32_16x16x32_bf16 v[26:29], v[146:149], v[222:225], v[26:29]
	v_mfma_f32_16x16x32_bf16 v[30:33], v[150:153], v[218:221], v[30:33]
	v_mfma_f32_16x16x32_bf16 v[30:33], v[154:157], v[222:225], v[30:33]
	v_mfma_f32_16x16x32_bf16 v[22:25], v[176:179], v[218:221], v[22:25]
	v_mfma_f32_16x16x32_bf16 v[22:25], v[180:183], v[222:225], v[22:25]
	v_mfma_f32_16x16x32_bf16 v[6:9], v[176:179], v[226:229], v[6:9]
	v_mfma_f32_16x16x32_bf16 v[6:9], v[180:183], v[230:233], v[6:9]
	v_mfma_f32_16x16x32_bf16 v[14:17], v[150:153], v[226:229], v[14:17]
	v_mfma_f32_16x16x32_bf16 v[14:17], v[154:157], v[230:233], v[14:17]
	v_mfma_f32_16x16x32_bf16 v[10:13], v[142:145], v[226:229], v[10:13]
	v_mfma_f32_16x16x32_bf16 v[10:13], v[146:149], v[230:233], v[10:13]
	v_mfma_f32_16x16x32_bf16 v[18:21], v[134:137], v[226:229], v[18:21]
	v_mfma_f32_16x16x32_bf16 v[18:21], v[138:141], v[230:233], v[18:21]
	s_barrier
; #define PG8_STAGE(bufoff, gbase, voff) do { _Pragma("unroll") for (int _i = 0; _i < 2; ++_i) \
;         __builtin_amdgcn_global_load_lds((const unsigned*)((const char*)(gbase) + (voff)[_i]), (PG8_LAS unsigned*)(lds + (bufoff) + ldsw + _i * 8192), 16, 0, 0); } while (0)
; #define PG8_LDA(dst, b, h) do { _Pragma("unroll") for (int m = 0; m < 4; ++m) _Pragma("unroll") for (int k = 0; k < 2; ++k) dst[m][k] = *(const PG8_LAS bf16x8*)(lds + PG8_SA(b, h) + aoff + m * 2048 + k * 1024); } while (0)
; #define PG8_LDB(dst, b, h) do { _Pragma("unroll") for (int n = 0; n < 2; ++n) _Pragma("unroll") for (int k = 0; k < 2; ++k) dst[n][k] = *(const PG8_LAS bf16x8*)(lds + PG8_SB(b, h) + boff + n * 2048 + k * 1024); } while (0)
; #define PG8_MMA(ai, bj, At, Bt) do { __builtin_amdgcn_s_setprio(1); _Pragma("unroll") for (int m = 0; m < 4; ++m) _Pragma("unroll") for (int n = 0; n < 2; ++n) _Pragma("unroll") for (int k = 0; k < 2; ++k) \
;         acc[ai][bj][m][n] = __builtin_amdgcn_mfma_f32_16x16x32_bf16(Bt[n][k], At[m][k], acc[ai][bj][m][n], 0, 0, 0); __builtin_amdgcn_s_setprio(0); } while (0)
; #define PG8_WAIT_V(n) asm volatile("s_waitcnt vmcnt(" #n ")" ::: "memory")
; #define PG8_WAIT_L(n) asm volatile("s_waitcnt lgkmcnt(" #n ")" ::: "memory")
; #define PG8_BAR __builtin_amdgcn_s_barrier()
; #define PG8_SCHED __builtin_amdgcn_sched_barrier(0)
; template <class Epi, class Sched, bool ALIGN_EPI = false, bool SP2 = false>
; __device__ __forceinline__ void gemm_phase(PG8_LAS unsigned char* lds, const Gemm g, const Sched& S, const Epi& E) {
;     ...
;         for (int t = 0; t < nt; t += 2) {
;             const bool last = (t == nt - 2);
;             const char* a1 = cA + (size_t)(t + 1) * kstep;
;             const char* a2 = last ? nA : cA + (size_t)(t + 2) * kstep; const char* b2 = last ? nB : cB + (size_t)(t + 2) * kstep;
;     ...
;             PG8_LDB(B0, 1, 0); PG8_LDB(B1, 1, 1); PG8_SCHED; PG8_LDA(At, 1, 0); PG8_STAGE(PG8_SA(0, 1), a2 + hstep, voffA);
;             PG8_WAIT_V(8); PG8_WAIT_L(0); PG8_BAR; PG8_MMA(0, 0, At, B0); PG8_MMA(0, 1, At, B1); PG8_BAR; PG8_SCHED;
;             PG8_LDA(At, 1, 1); PG8_STAGE(PG8_SB(1, 0), b3, voffB); PG8_STAGE(PG8_SB(1, 1), b3 + hstep, voffB); PG8_STAGE(PG8_SA(1, 0), a3, voffA);
;             PG8_WAIT_V(8); PG8_WAIT_L(0); PG8_BAR; PG8_MMA(1, 0, At, B0); PG8_MMA(1, 1, At, B1); PG8_BAR; PG8_SCHED;
	s_add_i32 s4, 0, 0x18000
	s_add_i32 s5, 0, 0x1c000
	ds_read_b128 v[134:137], v236
	ds_read_b128 v[138:141], v236 offset:1024
	ds_read_b128 v[142:145], v236 offset:2048
	ds_read_b128 v[146:149], v236 offset:3072
	ds_read_b128 v[150:153], v237
	ds_read_b128 v[154:157], v237 offset:1024
	ds_read_b128 v[176:179], v237 offset:2048
	ds_read_b128 v[180:183], v237 offset:3072
	s_add_u32 s34, s52, 0x80000
	s_addc_u32 s35, s53, 0
	s_mov_b32 m0, s56
	ds_read_b128 v[184:187], v188 offset:32768
	ds_read_b128 v[190:193], v188 offset:33792
	ds_read_b128 v[210:213], v188 offset:34816
	ds_read_b128 v[214:217], v188 offset:35840
	ds_read_b128 v[218:221], v188 offset:36864
	ds_read_b128 v[222:225], v188 offset:37888
	ds_read_b128 v[226:229], v188 offset:38912
	global_load_lds_dwordx4 v170, s[34:35]
	s_mov_b32 m0, s57
	ds_read_b128 v[230:233], v188 offset:39936
	global_load_lds_dwordx4 v168, s[34:35]
	s_waitcnt vmcnt(8)
	s_waitcnt lgkmcnt(0)
	s_barrier
	v_mfma_f32_16x16x32_bf16 v[122:125], v[134:137], v[184:187], v[122:125]
	v_mfma_f32_16x16x32_bf16 v[122:125], v[138:141], v[190:193], v[122:125]
	v_mfma_f32_16x16x32_bf16 v[118:121], v[142:145], v[184:187], v[118:121]
	v_mfma_f32_16x16x32_bf16 v[118:121], v[146:149], v[190:193], v[118:121]
	v_mfma_f32_16x16x32_bf16 v[130:133], v[150:153], v[184:187], v[130:133]
	v_mfma_f32_16x16x32_bf16 v[130:133], v[154:157], v[190:193], v[130:133]
	v_mfma_f32_16x16x32_bf16 v[126:129], v[176:179], v[184:187], v[126:129]
	v_mfma_f32_16x16x32_bf16 v[126:129], v[180:183], v[190:193], v[126:129]
	v_mfma_f32_16x16x32_bf16 v[102:105], v[176:179], v[210:213], v[102:105]
	v_mfma_f32_16x16x32_bf16 v[102:105], v[180:183], v[214:217], v[102:105]
	v_mfma_f32_16x16x32_bf16 v[110:113], v[150:153], v[210:213], v[110:113]
	v_mfma_f32_16x16x32_bf16 v[110:113], v[154:157], v[214:217], v[110:113]
	v_mfma_f32_16x16x32_bf16 v[106:109], v[142:145], v[210:213], v[106:109]
	v_mfma_f32_16x16x32_bf16 v[106:109], v[146:149], v[214:217], v[106:109]
	v_mfma_f32_16x16x32_bf16 v[114:117], v[134:137], v[210:213], v[114:117]
	v_mfma_f32_16x16x32_bf16 v[114:117], v[138:141], v[214:217], v[114:117]
	v_mfma_f32_16x16x32_bf16 v[98:101], v[134:137], v[218:221], v[98:101]
	v_mfma_f32_16x16x32_bf16 v[98:101], v[138:141], v[222:225], v[98:101]
	v_mfma_f32_16x16x32_bf16 v[90:93], v[142:145], v[218:221], v[90:93]
	v_mfma_f32_16x16x32_bf16 v[90:93], v[146:149], v[222:225], v[90:93]
	v_mfma_f32_16x16x32_bf16 v[94:97], v[150:153], v[218:221], v[94:97]
	v_mfma_f32_16x16x32_bf16 v[94:97], v[154:157], v[222:225], v[94:97]
	v_mfma_f32_16x16x32_bf16 v[86:89], v[176:179], v[218:221], v[86:89]
	v_mfma_f32_16x16x32_bf16 v[86:89], v[180:183], v[222:225], v[86:89]
	v_mfma_f32_16x16x32_bf16 v[70:73], v[176:179], v[226:229], v[70:73]
	v_mfma_f32_16x16x32_bf16 v[70:73], v[180:183], v[230:233], v[70:73]
	v_mfma_f32_16x16x32_bf16 v[78:81], v[150:153], v[226:229], v[78:81]
	v_mfma_f32_16x16x32_bf16 v[78:81], v[154:157], v[230:233], v[78:81]
	v_mfma_f32_16x16x32_bf16 v[74:77], v[142:145], v[226:229], v[74:77]
	v_mfma_f32_16x16x32_bf16 v[74:77], v[146:149], v[230:233], v[74:77]
	v_mfma_f32_16x16x32_bf16 v[82:85], v[134:137], v[226:229], v[82:85]
	v_mfma_f32_16x16x32_bf16 v[82:85], v[138:141], v[230:233], v[82:85]
	s_barrier
	s_add_i32 s4, s4, s24
	s_add_i32 m0, s4, 0xffffff80
	ds_read_b128 v[184:187], v188 offset:49152
	ds_read_b128 v[190:193], v188 offset:50176
	ds_read_b128 v[210:213], v188 offset:51200
	ds_read_b128 v[214:217], v188 offset:52224
	global_load_lds_dwordx4 v4, s[48:49] offset:128
	s_add_i32 m0, s4, 0x1f80
	s_add_u32 s34, s48, 0x80080
	s_addc_u32 s35, s49, 0
	s_add_i32 s4, s5, s24
	global_load_lds_dwordx4 v2, s[48:49] offset:128
	s_mov_b32 m0, s4
	ds_read_b128 v[218:221], v188 offset:53248
	global_load_lds_dwordx4 v4, s[34:35]
	s_add_i32 m0, s4, 0x2000
	ds_read_b128 v[222:225], v188 offset:54272
	global_load_lds_dwordx4 v2, s[34:35]
	s_add_i32 m0, s60, 0xffffff80
	ds_read_b128 v[226:229], v188 offset:55296
	global_load_lds_dwordx4 v170, s[52:53] offset:128
	s_add_i32 m0, s61, 0xffffff80
	ds_read_b128 v[230:233], v188 offset:56320
	global_load_lds_dwordx4 v168, s[52:53] offset:128
	s_waitcnt vmcnt(8)
	s_waitcnt lgkmcnt(0)
	s_barrier
	v_mfma_f32_16x16x32_bf16 v[58:61], v[134:137], v[184:187], v[58:61]
	v_mfma_f32_16x16x32_bf16 v[58:61], v[138:141], v[190:193], v[58:61]
	v_mfma_f32_16x16x32_bf16 v[54:57], v[142:145], v[184:187], v[54:57]
	v_mfma_f32_16x16x32_bf16 v[54:57], v[146:149], v[190:193], v[54:57]
	v_mfma_f32_16x16x32_bf16 v[66:69], v[150:153], v[184:187], v[66:69]
	v_mfma_f32_16x16x32_bf16 v[66:69], v[154:157], v[190:193], v[66:69]
	v_mfma_f32_16x16x32_bf16 v[62:65], v[176:179], v[184:187], v[62:65]
	v_mfma_f32_16x16x32_bf16 v[62:65], v[180:183], v[190:193], v[62:65]
	v_mfma_f32_16x16x32_bf16 v[38:41], v[176:179], v[210:213], v[38:41]
	v_mfma_f32_16x16x32_bf16 v[38:41], v[180:183], v[214:217], v[38:41]
	v_mfma_f32_16x16x32_bf16 v[46:49], v[150:153], v[210:213], v[46:49]
	v_mfma_f32_16x16x32_bf16 v[46:49], v[154:157], v[214:217], v[46:49]
	v_mfma_f32_16x16x32_bf16 v[42:45], v[142:145], v[210:213], v[42:45]
	v_mfma_f32_16x16x32_bf16 v[42:45], v[146:149], v[214:217], v[42:45]
	v_mfma_f32_16x16x32_bf16 v[50:53], v[134:137], v[210:213], v[50:53]
	v_mfma_f32_16x16x32_bf16 v[50:53], v[138:141], v[214:217], v[50:53]
	v_mfma_f32_16x16x32_bf16 v[34:37], v[134:137], v[218:221], v[34:37]
	v_mfma_f32_16x16x32_bf16 v[34:37], v[138:141], v[222:225], v[34:37]
	v_mfma_f32_16x16x32_bf16 v[26:29], v[142:145], v[218:221], v[26:29]
	v_mfma_f32_16x16x32_bf16 v[26:29], v[146:149], v[222:225], v[26:29]
	v_mfma_f32_16x16x32_bf16 v[30:33], v[150:153], v[218:221], v[30:33]
	v_mfma_f32_16x16x32_bf16 v[30:33], v[154:157], v[222:225], v[30:33]
	v_mfma_f32_16x16x32_bf16 v[22:25], v[176:179], v[218:221], v[22:25]
	v_mfma_f32_16x16x32_bf16 v[22:25], v[180:183], v[222:225], v[22:25]
	v_mfma_f32_16x16x32_bf16 v[6:9], v[176:179], v[226:229], v[6:9]
	v_mfma_f32_16x16x32_bf16 v[6:9], v[180:183], v[230:233], v[6:9]
	v_mfma_f32_16x16x32_bf16 v[14:17], v[150:153], v[226:229], v[14:17]
	v_mfma_f32_16x16x32_bf16 v[14:17], v[154:157], v[230:233], v[14:17]
	v_mfma_f32_16x16x32_bf16 v[10:13], v[142:145], v[226:229], v[10:13]
	v_mfma_f32_16x16x32_bf16 v[10:13], v[146:149], v[230:233], v[10:13]
	v_mfma_f32_16x16x32_bf16 v[18:21], v[134:137], v[226:229], v[18:21]
	v_mfma_f32_16x16x32_bf16 v[18:21], v[138:141], v[230:233], v[18:21]
	s_barrier
	s_add_i32 s20, s20, 2
	s_add_u32 s50, s50, 0x100
	s_addc_u32 s51, s51, 0
	s_add_u32 s69, s69, 0x100
	s_addc_u32 s71, s71, 0
	s_cmp_gt_u32 s20, 29
	s_cbranch_scc0 .LBB0_1738
	s_and_b64 vcc, exec, s[40:41]
	s_cbranch_vccz .LBB0_1741
	s_barrier
